# GEMM K-loops: back-edge counter/pointer updates and exit compare moved ahead of the loop-back barrier (back-edge rotation)
# speedup vs baseline: 1.0052x; 1.0052x over previous
; #define PG8_STAGE(bufoff, gbase, voff) do { _Pragma("unroll") for (int _i = 0; _i < 2; ++_i) \
;         __builtin_amdgcn_global_load_lds((const unsigned*)((const char*)(gbase) + (voff)[_i]), (PG8_LAS unsigned*)(lds + (bufoff) + ldsw + _i * 8192), 16, 0, 0); } while (0)
; #define PG8_LDA(dst, b, h) do { _Pragma("unroll") for (int m = 0; m < 4; ++m) _Pragma("unroll") for (int k = 0; k < 2; ++k) dst[m][k] = *(const PG8_LAS bf16x8*)(lds + PG8_SA(b, h) + aoff + m * 2048 + k * 1024); } while (0)
; #define PG8_LDB(dst, b, h) do { _Pragma("unroll") for (int n = 0; n < 2; ++n) _Pragma("unroll") for (int k = 0; k < 2; ++k) dst[n][k] = *(const PG8_LAS bf16x8*)(lds + PG8_SB(b, h) + boff + n * 2048 + k * 1024); } while (0)
; #define PG8_MMA(ai, bj, At, Bt) do { __builtin_amdgcn_s_setprio(1); _Pragma("unroll") for (int m = 0; m < 4; ++m) _Pragma("unroll") for (int n = 0; n < 2; ++n) _Pragma("unroll") for (int k = 0; k < 2; ++k) \
;         acc[ai][bj][m][n] = __builtin_amdgcn_mfma_f32_16x16x32_bf16(Bt[n][k], At[m][k], acc[ai][bj][m][n], 0, 0, 0); __builtin_amdgcn_s_setprio(0); } while (0)
; #define PG8_WAIT_V(n) asm volatile("s_waitcnt vmcnt(" #n ")" ::: "memory")
; #define PG8_WAIT_L(n) asm volatile("s_waitcnt lgkmcnt(" #n ")" ::: "memory")
; #define PG8_BAR __builtin_amdgcn_s_barrier()
; #define PG8_SCHED __builtin_amdgcn_sched_barrier(0)
; template <class Epi>
; DI void gemm_phase(PG8_LAS unsigned char* lds, const Gemm g, const StaticOrder& S, const Epi& E) {
;     ...
;         for (int t = 0; t < nt; t += 2) {
;             const bool last = (t == nt - 2);
;             const char* a1 = cA + (size_t)(t + 1) * kstep;
;             const char* a2 = last ? nA : cA + (size_t)(t + 2) * kstep; const char* b2 = last ? nB : cB + (size_t)(t + 2) * kstep;
;             const char* a3 = a2 + kstep; const char* b3 = b2 + kstep;
;             PG8_LDB(B0, 0, 0); PG8_LDB(B1, 0, 1); PG8_SCHED; PG8_LDA(At, 0, 0); PG8_STAGE(PG8_SA(1, 1), a1 + hstepA, voffA);
;             PG8_WAIT_V(8); PG8_WAIT_L(0); PG8_BAR; PG8_MMA(0, 0, At, B0); PG8_MMA(0, 1, At, B1); PG8_BAR; PG8_SCHED;
;             PG8_LDA(At, 0, 1); PG8_STAGE(PG8_SB(0, 0), b2, voffB); PG8_STAGE(PG8_SB(0, 1), b2 + hstepB, voffB); PG8_STAGE(PG8_SA(0, 0), a2, voffA);
;             PG8_WAIT_V(8); PG8_WAIT_L(0); PG8_BAR; PG8_MMA(1, 0, At, B0); PG8_MMA(1, 1, At, B1); PG8_BAR; PG8_SCHED;
.LBB0_283:
	ds_read_b128 v[92:95], v173
	ds_read_b128 v[96:99], v173 offset:1024
	ds_read_b128 v[112:115], v173 offset:2048
	ds_read_b128 v[116:119], v173 offset:3072
	ds_read_b128 v[162:165], v174
	ds_read_b128 v[166:169], v174 offset:1024
	ds_read_b128 v[176:179], v174 offset:2048
	ds_read_b128 v[180:183], v174 offset:3072
	s_add_u32 s18, s28, 0xfffc0080
	s_addc_u32 s19, s29, -1
	s_cmp_eq_u32 s53, 12
	s_cselect_b32 s35, s6, s19
	s_cselect_b32 s34, s17, s18
	s_cselect_b32 s31, s15, s52
	s_cselect_b32 s30, s50, s51
	v_lshl_add_u64 v[216:217], s[28:29], 0, v[154:155]
	s_add_i32 m0, s38, 0xc000
	ds_read_b128 v[184:187], v175
	ds_read_b128 v[188:191], v175 offset:1024
	ds_read_b128 v[192:195], v175 offset:2048
	ds_read_b128 v[196:199], v175 offset:3072
	ds_read_b128 v[200:203], v175 offset:4096
	ds_read_b128 v[204:207], v175 offset:5120
	ds_read_b128 v[208:211], v175 offset:6144
	ds_read_b128 v[212:215], v175 offset:7168
	global_load_lds_dwordx4 v[216:217], off
	v_lshl_add_u64 v[216:217], s[28:29], 0, v[156:157]
	s_add_i32 m0, s38, 0xe000
	s_nop 0
	global_load_lds_dwordx4 v[216:217], off
	s_waitcnt vmcnt(8)
	s_waitcnt lgkmcnt(0)
	s_barrier
	s_setprio 1
	s_waitcnt lgkmcnt(0)
	v_mfma_f32_16x16x32_bf16 v[140:143], v[92:95], v[184:187], v[140:143]
	v_mfma_f32_16x16x32_bf16 v[136:139], v[112:115], v[184:187], v[136:139]
	v_mfma_f32_16x16x32_bf16 v[124:127], v[92:95], v[192:195], v[124:127]
	v_mfma_f32_16x16x32_bf16 v[120:123], v[112:115], v[192:195], v[120:123]
	v_mfma_f32_16x16x32_bf16 v[100:103], v[92:95], v[200:203], v[100:103]
	v_mfma_f32_16x16x32_bf16 v[88:91], v[112:115], v[200:203], v[88:91]
	v_mfma_f32_16x16x32_bf16 v[76:79], v[92:95], v[208:211], v[76:79]
	v_mfma_f32_16x16x32_bf16 v[72:75], v[112:115], v[208:211], v[72:75]
	v_mfma_f32_16x16x32_bf16 v[140:143], v[96:99], v[188:191], v[140:143]
	v_mfma_f32_16x16x32_bf16 v[136:139], v[116:119], v[188:191], v[136:139]
	v_mfma_f32_16x16x32_bf16 v[124:127], v[96:99], v[196:199], v[124:127]
	v_mfma_f32_16x16x32_bf16 v[120:123], v[116:119], v[196:199], v[120:123]
	v_mfma_f32_16x16x32_bf16 v[100:103], v[96:99], v[204:207], v[100:103]
	v_mfma_f32_16x16x32_bf16 v[88:91], v[116:119], v[204:207], v[88:91]
	v_mfma_f32_16x16x32_bf16 v[76:79], v[96:99], v[212:215], v[76:79]
	v_mfma_f32_16x16x32_bf16 v[72:75], v[116:119], v[212:215], v[72:75]
	s_setprio 0
	s_setprio 1
	v_mfma_f32_16x16x32_bf16 v[132:135], v[162:165], v[184:187], v[132:135]
	v_mfma_f32_16x16x32_bf16 v[128:131], v[176:179], v[184:187], v[128:131]
	v_mfma_f32_16x16x32_bf16 v[108:111], v[162:165], v[192:195], v[108:111]
	v_mfma_f32_16x16x32_bf16 v[104:107], v[176:179], v[192:195], v[104:107]
	v_mfma_f32_16x16x32_bf16 v[84:87], v[162:165], v[200:203], v[84:87]
	v_mfma_f32_16x16x32_bf16 v[80:83], v[176:179], v[200:203], v[80:83]
	v_mfma_f32_16x16x32_bf16 v[68:71], v[162:165], v[208:211], v[68:71]
	v_mfma_f32_16x16x32_bf16 v[64:67], v[176:179], v[208:211], v[64:67]
	v_mfma_f32_16x16x32_bf16 v[132:135], v[166:169], v[188:191], v[132:135]
	v_mfma_f32_16x16x32_bf16 v[128:131], v[180:183], v[188:191], v[128:131]
	v_mfma_f32_16x16x32_bf16 v[108:111], v[166:169], v[196:199], v[108:111]
	v_mfma_f32_16x16x32_bf16 v[104:107], v[180:183], v[196:199], v[104:107]
	v_mfma_f32_16x16x32_bf16 v[84:87], v[166:169], v[204:207], v[84:87]
	v_mfma_f32_16x16x32_bf16 v[80:83], v[180:183], v[204:207], v[80:83]
	v_mfma_f32_16x16x32_bf16 v[68:71], v[166:169], v[212:215], v[68:71]
	v_mfma_f32_16x16x32_bf16 v[64:67], v[180:183], v[212:215], v[64:67]
	s_setprio 0
	s_barrier
	s_add_i32 s18, s47, s36
	v_lshl_add_u64 v[216:217], s[30:31], 0, v[148:149]
	s_mov_b32 m0, s18
	ds_read_b128 v[184:187], v175 offset:16384
	ds_read_b128 v[188:191], v175 offset:17408
	ds_read_b128 v[192:195], v175 offset:18432
	ds_read_b128 v[196:199], v175 offset:19456
	ds_read_b128 v[200:203], v175 offset:20480
	ds_read_b128 v[204:207], v175 offset:21504
	ds_read_b128 v[208:211], v175 offset:22528
	ds_read_b128 v[212:215], v175 offset:23552
	global_load_lds_dwordx4 v[216:217], off
	s_add_i32 m0, s18, 0x2000
	s_add_u32 s56, s30, 0x40000
	v_lshl_add_u64 v[218:219], s[30:31], 0, v[144:145]
	s_addc_u32 s57, s31, 0
	s_add_i32 s18, s48, s36
	global_load_lds_dwordx4 v[218:219], off
	v_lshl_add_u64 v[220:221], s[56:57], 0, v[148:149]
	s_mov_b32 m0, s18
	v_lshl_add_u64 v[222:223], s[34:35], 0, v[146:147]
	global_load_lds_dwordx4 v[220:221], off
	v_lshl_add_u64 v[220:221], s[56:57], 0, v[144:145]
	s_add_i32 m0, s18, 0x2000
	s_nop 0
	global_load_lds_dwordx4 v[220:221], off
	v_lshl_add_u64 v[220:221], s[34:35], 0, v[150:151]
	s_mov_b32 m0, s38
	s_nop 0
	global_load_lds_dwordx4 v[220:221], off
	s_mov_b32 m0, s39
	s_nop 0
	global_load_lds_dwordx4 v[222:223], off
	s_waitcnt vmcnt(8)
	s_waitcnt lgkmcnt(0)
	s_barrier
; #define PG8_STAGE(bufoff, gbase, voff) do { _Pragma("unroll") for (int _i = 0; _i < 2; ++_i) \
;         __builtin_amdgcn_global_load_lds((const unsigned*)((const char*)(gbase) + (voff)[_i]), (PG8_LAS unsigned*)(lds + (bufoff) + ldsw + _i * 8192), 16, 0, 0); } while (0)
; #define PG8_LDA(dst, b, h) do { _Pragma("unroll") for (int m = 0; m < 4; ++m) _Pragma("unroll") for (int k = 0; k < 2; ++k) dst[m][k] = *(const PG8_LAS bf16x8*)(lds + PG8_SA(b, h) + aoff + m * 2048 + k * 1024); } while (0)
; #define PG8_LDB(dst, b, h) do { _Pragma("unroll") for (int n = 0; n < 2; ++n) _Pragma("unroll") for (int k = 0; k < 2; ++k) dst[n][k] = *(const PG8_LAS bf16x8*)(lds + PG8_SB(b, h) + boff + n * 2048 + k * 1024); } while (0)
; #define PG8_MMA(ai, bj, At, Bt) do { __builtin_amdgcn_s_setprio(1); _Pragma("unroll") for (int m = 0; m < 4; ++m) _Pragma("unroll") for (int n = 0; n < 2; ++n) _Pragma("unroll") for (int k = 0; k < 2; ++k) \
;         acc[ai][bj][m][n] = __builtin_amdgcn_mfma_f32_16x16x32_bf16(Bt[n][k], At[m][k], acc[ai][bj][m][n], 0, 0, 0); __builtin_amdgcn_s_setprio(0); } while (0)
; #define PG8_WAIT_V(n) asm volatile("s_waitcnt vmcnt(" #n ")" ::: "memory")
; #define PG8_WAIT_L(n) asm volatile("s_waitcnt lgkmcnt(" #n ")" ::: "memory")
; #define PG8_BAR __builtin_amdgcn_s_barrier()
; #define PG8_SCHED __builtin_amdgcn_sched_barrier(0)
; template <class Epi>
; DI void gemm_phase(PG8_LAS unsigned char* lds, const Gemm g, const StaticOrder& S, const Epi& E) {
;     ...
;             PG8_WAIT_V(8); PG8_WAIT_L(0); PG8_BAR; PG8_MMA(1, 0, At, B0); PG8_MMA(1, 1, At, B1); PG8_BAR; PG8_SCHED;
;             PG8_LDB(B0, 1, 0); PG8_LDB(B1, 1, 1); PG8_SCHED; PG8_LDA(At, 1, 0); PG8_STAGE(PG8_SA(0, 1), a2 + hstepA, voffA);
;             PG8_WAIT_V(8); PG8_WAIT_L(0); PG8_BAR; PG8_MMA(0, 0, At, B0); PG8_MMA(0, 1, At, B1); PG8_BAR; PG8_SCHED;
	s_setprio 1
	s_waitcnt lgkmcnt(0)
	v_mfma_f32_16x16x32_bf16 v[60:63], v[92:95], v[184:187], v[60:63]
	v_mfma_f32_16x16x32_bf16 v[56:59], v[112:115], v[184:187], v[56:59]
	v_mfma_f32_16x16x32_bf16 v[44:47], v[92:95], v[192:195], v[44:47]
	v_mfma_f32_16x16x32_bf16 v[40:43], v[112:115], v[192:195], v[40:43]
	v_mfma_f32_16x16x32_bf16 v[28:31], v[92:95], v[200:203], v[28:31]
	v_mfma_f32_16x16x32_bf16 v[24:27], v[112:115], v[200:203], v[24:27]
	v_mfma_f32_16x16x32_bf16 v[12:15], v[92:95], v[208:211], v[12:15]
	v_mfma_f32_16x16x32_bf16 v[8:11], v[112:115], v[208:211], v[8:11]
	v_mfma_f32_16x16x32_bf16 v[60:63], v[96:99], v[188:191], v[60:63]
	v_mfma_f32_16x16x32_bf16 v[56:59], v[116:119], v[188:191], v[56:59]
	v_mfma_f32_16x16x32_bf16 v[44:47], v[96:99], v[196:199], v[44:47]
	v_mfma_f32_16x16x32_bf16 v[40:43], v[116:119], v[196:199], v[40:43]
	v_mfma_f32_16x16x32_bf16 v[28:31], v[96:99], v[204:207], v[28:31]
	v_mfma_f32_16x16x32_bf16 v[24:27], v[116:119], v[204:207], v[24:27]
	v_mfma_f32_16x16x32_bf16 v[12:15], v[96:99], v[212:215], v[12:15]
	v_mfma_f32_16x16x32_bf16 v[8:11], v[116:119], v[212:215], v[8:11]
	s_setprio 0
	s_setprio 1
	v_mfma_f32_16x16x32_bf16 v[52:55], v[162:165], v[184:187], v[52:55]
	v_mfma_f32_16x16x32_bf16 v[48:51], v[176:179], v[184:187], v[48:51]
	v_mfma_f32_16x16x32_bf16 v[36:39], v[162:165], v[192:195], v[36:39]
	v_mfma_f32_16x16x32_bf16 v[32:35], v[176:179], v[192:195], v[32:35]
	v_mfma_f32_16x16x32_bf16 v[20:23], v[162:165], v[200:203], v[20:23]
	v_mfma_f32_16x16x32_bf16 v[16:19], v[176:179], v[200:203], v[16:19]
	v_mfma_f32_16x16x32_bf16 v[4:7], v[162:165], v[208:211], v[4:7]
	v_mfma_f32_16x16x32_bf16 v[0:3], v[176:179], v[208:211], v[0:3]
	v_mfma_f32_16x16x32_bf16 v[52:55], v[166:169], v[188:191], v[52:55]
	v_mfma_f32_16x16x32_bf16 v[48:51], v[180:183], v[188:191], v[48:51]
	v_mfma_f32_16x16x32_bf16 v[36:39], v[166:169], v[196:199], v[36:39]
	v_mfma_f32_16x16x32_bf16 v[32:35], v[180:183], v[196:199], v[32:35]
	v_mfma_f32_16x16x32_bf16 v[20:23], v[166:169], v[204:207], v[20:23]
	v_mfma_f32_16x16x32_bf16 v[16:19], v[180:183], v[204:207], v[16:19]
	v_mfma_f32_16x16x32_bf16 v[4:7], v[166:169], v[212:215], v[4:7]
	v_mfma_f32_16x16x32_bf16 v[0:3], v[180:183], v[212:215], v[0:3]
	s_setprio 0
	s_barrier
	s_add_i32 s18, 16, 0x18000
	s_add_i32 s19, 16, 0x1c000
	v_add_u32_e32 v116, s18, v172
	v_add_u32_e32 v152, s19, v172
	ds_read_b128 v[92:95], v116
	ds_read_b128 v[96:99], v116 offset:1024
	ds_read_b128 v[112:115], v116 offset:2048
	ds_read_b128 v[116:119], v116 offset:3072
	ds_read_b128 v[162:165], v152
	ds_read_b128 v[166:169], v152 offset:1024
	ds_read_b128 v[176:179], v152 offset:2048
	ds_read_b128 v[180:183], v152 offset:3072
	s_add_u32 s34, s34, 0x40000
	s_addc_u32 s35, s35, 0
	s_mov_b32 m0, s40
	v_lshl_add_u64 v[226:227], s[34:35], 0, v[150:151]
	ds_read_b128 v[184:187], v175 offset:32768
	ds_read_b128 v[188:191], v175 offset:33792
	ds_read_b128 v[192:195], v175 offset:34816
	ds_read_b128 v[196:199], v175 offset:35840
	ds_read_b128 v[200:203], v175 offset:36864
	ds_read_b128 v[204:207], v175 offset:37888
	ds_read_b128 v[208:211], v175 offset:38912
	ds_read_b128 v[212:215], v175 offset:39936
	global_load_lds_dwordx4 v[226:227], off
	v_lshl_add_u64 v[226:227], s[34:35], 0, v[146:147]
	s_mov_b32 m0, s41
	s_nop 0
	global_load_lds_dwordx4 v[226:227], off
	s_waitcnt vmcnt(8)
	s_waitcnt lgkmcnt(0)
	s_barrier
	s_setprio 1
	s_waitcnt lgkmcnt(0)
	v_mfma_f32_16x16x32_bf16 v[140:143], v[92:95], v[184:187], v[140:143]
	v_mfma_f32_16x16x32_bf16 v[136:139], v[112:115], v[184:187], v[136:139]
	v_mfma_f32_16x16x32_bf16 v[124:127], v[92:95], v[192:195], v[124:127]
	v_mfma_f32_16x16x32_bf16 v[120:123], v[112:115], v[192:195], v[120:123]
	v_mfma_f32_16x16x32_bf16 v[100:103], v[92:95], v[200:203], v[100:103]
	v_mfma_f32_16x16x32_bf16 v[88:91], v[112:115], v[200:203], v[88:91]
	v_mfma_f32_16x16x32_bf16 v[76:79], v[92:95], v[208:211], v[76:79]
	v_mfma_f32_16x16x32_bf16 v[72:75], v[112:115], v[208:211], v[72:75]
	v_mfma_f32_16x16x32_bf16 v[140:143], v[96:99], v[188:191], v[140:143]
	v_mfma_f32_16x16x32_bf16 v[136:139], v[116:119], v[188:191], v[136:139]
	v_mfma_f32_16x16x32_bf16 v[124:127], v[96:99], v[196:199], v[124:127]
	v_mfma_f32_16x16x32_bf16 v[120:123], v[116:119], v[196:199], v[120:123]
	v_mfma_f32_16x16x32_bf16 v[100:103], v[96:99], v[204:207], v[100:103]
	v_mfma_f32_16x16x32_bf16 v[88:91], v[116:119], v[204:207], v[88:91]
	v_mfma_f32_16x16x32_bf16 v[76:79], v[96:99], v[212:215], v[76:79]
	v_mfma_f32_16x16x32_bf16 v[72:75], v[116:119], v[212:215], v[72:75]
	s_setprio 0
	s_setprio 1
	v_mfma_f32_16x16x32_bf16 v[132:135], v[162:165], v[184:187], v[132:135]
	v_mfma_f32_16x16x32_bf16 v[128:131], v[176:179], v[184:187], v[128:131]
	v_mfma_f32_16x16x32_bf16 v[108:111], v[162:165], v[192:195], v[108:111]
	v_mfma_f32_16x16x32_bf16 v[104:107], v[176:179], v[192:195], v[104:107]
	v_mfma_f32_16x16x32_bf16 v[84:87], v[162:165], v[200:203], v[84:87]
	v_mfma_f32_16x16x32_bf16 v[80:83], v[176:179], v[200:203], v[80:83]
	v_mfma_f32_16x16x32_bf16 v[68:71], v[162:165], v[208:211], v[68:71]
	v_mfma_f32_16x16x32_bf16 v[64:67], v[176:179], v[208:211], v[64:67]
	v_mfma_f32_16x16x32_bf16 v[132:135], v[166:169], v[188:191], v[132:135]
	v_mfma_f32_16x16x32_bf16 v[128:131], v[180:183], v[188:191], v[128:131]
	v_mfma_f32_16x16x32_bf16 v[108:111], v[166:169], v[196:199], v[108:111]
	v_mfma_f32_16x16x32_bf16 v[104:107], v[180:183], v[196:199], v[104:107]
	v_mfma_f32_16x16x32_bf16 v[84:87], v[166:169], v[204:207], v[84:87]
	v_mfma_f32_16x16x32_bf16 v[80:83], v[180:183], v[204:207], v[80:83]
	v_mfma_f32_16x16x32_bf16 v[68:71], v[166:169], v[212:215], v[68:71]
	v_mfma_f32_16x16x32_bf16 v[64:67], v[180:183], v[212:215], v[64:67]
	s_setprio 0
	s_barrier
; #define PG8_STAGE(bufoff, gbase, voff) do { _Pragma("unroll") for (int _i = 0; _i < 2; ++_i) \
;         __builtin_amdgcn_global_load_lds((const unsigned*)((const char*)(gbase) + (voff)[_i]), (PG8_LAS unsigned*)(lds + (bufoff) + ldsw + _i * 8192), 16, 0, 0); } while (0)
; #define PG8_LDA(dst, b, h) do { _Pragma("unroll") for (int m = 0; m < 4; ++m) _Pragma("unroll") for (int k = 0; k < 2; ++k) dst[m][k] = *(const PG8_LAS bf16x8*)(lds + PG8_SA(b, h) + aoff + m * 2048 + k * 1024); } while (0)
; #define PG8_MMA(ai, bj, At, Bt) do { __builtin_amdgcn_s_setprio(1); _Pragma("unroll") for (int m = 0; m < 4; ++m) _Pragma("unroll") for (int n = 0; n < 2; ++n) _Pragma("unroll") for (int k = 0; k < 2; ++k) \
;         acc[ai][bj][m][n] = __builtin_amdgcn_mfma_f32_16x16x32_bf16(Bt[n][k], At[m][k], acc[ai][bj][m][n], 0, 0, 0); __builtin_amdgcn_s_setprio(0); } while (0)
; #define PG8_WAIT_V(n) asm volatile("s_waitcnt vmcnt(" #n ")" ::: "memory")
; #define PG8_WAIT_L(n) asm volatile("s_waitcnt lgkmcnt(" #n ")" ::: "memory")
; #define PG8_BAR __builtin_amdgcn_s_barrier()
; #define PG8_SCHED __builtin_amdgcn_sched_barrier(0)
; template <class Epi>
; DI void gemm_phase(PG8_LAS unsigned char* lds, const Gemm g, const StaticOrder& S, const Epi& E) {
;     ...
;             PG8_LDA(At, 1, 1); PG8_STAGE(PG8_SB(1, 0), b3, voffB); PG8_STAGE(PG8_SB(1, 1), b3 + hstepB, voffB); PG8_STAGE(PG8_SA(1, 0), a3, voffA);
;             PG8_WAIT_V(8); PG8_WAIT_L(0); PG8_BAR; PG8_MMA(1, 0, At, B0); PG8_MMA(1, 1, At, B1); PG8_BAR; PG8_SCHED;
;         }
;         if (wr == 0) PG8_BAR;
	s_add_i32 s18, s18, s36
	v_lshl_add_u64 v[216:217], v[216:217], 0, s[10:11]
	s_mov_b32 m0, s18
	ds_read_b128 v[184:187], v175 offset:49152
	ds_read_b128 v[188:191], v175 offset:50176
	ds_read_b128 v[192:195], v175 offset:51200
	ds_read_b128 v[196:199], v175 offset:52224
	ds_read_b128 v[200:203], v175 offset:53248
	ds_read_b128 v[204:207], v175 offset:54272
	ds_read_b128 v[208:211], v175 offset:55296
	ds_read_b128 v[212:215], v175 offset:56320
	global_load_lds_dwordx4 v[216:217], off
	s_add_i32 m0, s18, 0x2000
	s_add_u32 s30, s30, 0x40080
	v_lshl_add_u64 v[216:217], v[218:219], 0, s[10:11]
	s_addc_u32 s31, s31, 0
	s_add_i32 s18, s19, s36
	global_load_lds_dwordx4 v[216:217], off
	v_lshl_add_u64 v[216:217], s[30:31], 0, v[148:149]
	s_mov_b32 m0, s18
	s_nop 0
	global_load_lds_dwordx4 v[216:217], off
	v_lshl_add_u64 v[216:217], s[30:31], 0, v[144:145]
	s_add_i32 m0, s18, 0x2000
	s_nop 0
	global_load_lds_dwordx4 v[216:217], off
	v_lshl_add_u64 v[216:217], v[220:221], 0, s[10:11]
	s_mov_b32 m0, s44
	s_nop 0
	global_load_lds_dwordx4 v[216:217], off
	v_lshl_add_u64 v[216:217], v[222:223], 0, s[10:11]
	s_mov_b32 m0, s45
	s_nop 0
	global_load_lds_dwordx4 v[216:217], off
	s_waitcnt vmcnt(8)
	s_waitcnt lgkmcnt(0)
	s_barrier
	s_setprio 1
	s_waitcnt lgkmcnt(0)
	v_mfma_f32_16x16x32_bf16 v[60:63], v[92:95], v[184:187], v[60:63]
	v_mfma_f32_16x16x32_bf16 v[56:59], v[112:115], v[184:187], v[56:59]
	v_mfma_f32_16x16x32_bf16 v[44:47], v[92:95], v[192:195], v[44:47]
	v_mfma_f32_16x16x32_bf16 v[40:43], v[112:115], v[192:195], v[40:43]
	v_mfma_f32_16x16x32_bf16 v[28:31], v[92:95], v[200:203], v[28:31]
	v_mfma_f32_16x16x32_bf16 v[24:27], v[112:115], v[200:203], v[24:27]
	v_mfma_f32_16x16x32_bf16 v[12:15], v[92:95], v[208:211], v[12:15]
	v_mfma_f32_16x16x32_bf16 v[8:11], v[112:115], v[208:211], v[8:11]
	v_mfma_f32_16x16x32_bf16 v[60:63], v[96:99], v[188:191], v[60:63]
	v_mfma_f32_16x16x32_bf16 v[56:59], v[116:119], v[188:191], v[56:59]
	v_mfma_f32_16x16x32_bf16 v[44:47], v[96:99], v[196:199], v[44:47]
	v_mfma_f32_16x16x32_bf16 v[40:43], v[116:119], v[196:199], v[40:43]
	v_mfma_f32_16x16x32_bf16 v[28:31], v[96:99], v[204:207], v[28:31]
	v_mfma_f32_16x16x32_bf16 v[24:27], v[116:119], v[204:207], v[24:27]
	v_mfma_f32_16x16x32_bf16 v[12:15], v[96:99], v[212:215], v[12:15]
	v_mfma_f32_16x16x32_bf16 v[8:11], v[116:119], v[212:215], v[8:11]
	s_setprio 0
	s_setprio 1
	v_mfma_f32_16x16x32_bf16 v[52:55], v[162:165], v[184:187], v[52:55]
	v_mfma_f32_16x16x32_bf16 v[48:51], v[176:179], v[184:187], v[48:51]
	v_mfma_f32_16x16x32_bf16 v[36:39], v[162:165], v[192:195], v[36:39]
	v_mfma_f32_16x16x32_bf16 v[32:35], v[176:179], v[192:195], v[32:35]
	v_mfma_f32_16x16x32_bf16 v[20:23], v[162:165], v[200:203], v[20:23]
	v_mfma_f32_16x16x32_bf16 v[16:19], v[176:179], v[200:203], v[16:19]
	v_mfma_f32_16x16x32_bf16 v[4:7], v[162:165], v[208:211], v[4:7]
	v_mfma_f32_16x16x32_bf16 v[0:3], v[176:179], v[208:211], v[0:3]
	v_mfma_f32_16x16x32_bf16 v[52:55], v[166:169], v[188:191], v[52:55]
	v_mfma_f32_16x16x32_bf16 v[48:51], v[180:183], v[188:191], v[48:51]
	v_mfma_f32_16x16x32_bf16 v[36:39], v[166:169], v[196:199], v[36:39]
	v_mfma_f32_16x16x32_bf16 v[32:35], v[180:183], v[196:199], v[32:35]
	v_mfma_f32_16x16x32_bf16 v[20:23], v[166:169], v[204:207], v[20:23]
	v_mfma_f32_16x16x32_bf16 v[16:19], v[180:183], v[204:207], v[16:19]
	v_mfma_f32_16x16x32_bf16 v[4:7], v[166:169], v[212:215], v[4:7]
	v_mfma_f32_16x16x32_bf16 v[0:3], v[180:183], v[212:215], v[0:3]
	s_setprio 0
	s_add_i32 s53, s53, 2
	s_add_u32 s28, s28, 0x100
	s_addc_u32 s29, s29, 0
	s_add_u32 s51, s51, 0x100
	s_addc_u32 s52, s52, 0
	s_cmp_gt_u32 s53, 13
	s_barrier
	s_cbranch_scc0 .LBB0_283
	s_and_b64 vcc, exec, s[12:13]
	s_cbranch_vccz .LBB0_286
	s_barrier

; #define PG8_STAGE(bufoff, gbase, voff) do { _Pragma("unroll") for (int _i = 0; _i < 2; ++_i) \
;         __builtin_amdgcn_global_load_lds((const unsigned*)((const char*)(gbase) + (voff)[_i]), (PG8_LAS unsigned*)(lds + (bufoff) + ldsw + _i * 8192), 16, 0, 0); } while (0)
; #define PG8_LDA(dst, b, h) do { _Pragma("unroll") for (int m = 0; m < 4; ++m) _Pragma("unroll") for (int k = 0; k < 2; ++k) dst[m][k] = *(const PG8_LAS bf16x8*)(lds + PG8_SA(b, h) + aoff + m * 2048 + k * 1024); } while (0)
; #define PG8_LDB(dst, b, h) do { _Pragma("unroll") for (int n = 0; n < 2; ++n) _Pragma("unroll") for (int k = 0; k < 2; ++k) dst[n][k] = *(const PG8_LAS bf16x8*)(lds + PG8_SB(b, h) + boff + n * 2048 + k * 1024); } while (0)
; #define PG8_MMA(ai, bj, At, Bt) do { __builtin_amdgcn_s_setprio(1); _Pragma("unroll") for (int m = 0; m < 4; ++m) _Pragma("unroll") for (int n = 0; n < 2; ++n) _Pragma("unroll") for (int k = 0; k < 2; ++k) \
;         acc[ai][bj][m][n] = __builtin_amdgcn_mfma_f32_16x16x32_bf16(Bt[n][k], At[m][k], acc[ai][bj][m][n], 0, 0, 0); __builtin_amdgcn_s_setprio(0); } while (0)
; #define PG8_WAIT_V(n) asm volatile("s_waitcnt vmcnt(" #n ")" ::: "memory")
; #define PG8_WAIT_L(n) asm volatile("s_waitcnt lgkmcnt(" #n ")" ::: "memory")
; #define PG8_BAR __builtin_amdgcn_s_barrier()
; #define PG8_SCHED __builtin_amdgcn_sched_barrier(0)
; template <class Epi>
; DI void gemm_phase(PG8_LAS unsigned char* lds, const Gemm g, const StaticOrder& S, const Epi& E) {
;     ...
;         for (int t = 0; t < nt; t += 2) {
;             const bool last = (t == nt - 2);
;             const char* a1 = cA + (size_t)(t + 1) * kstep;
;             const char* a2 = last ? nA : cA + (size_t)(t + 2) * kstep; const char* b2 = last ? nB : cB + (size_t)(t + 2) * kstep;
;             const char* a3 = a2 + kstep; const char* b3 = b2 + kstep;
;             PG8_LDB(B0, 0, 0); PG8_LDB(B1, 0, 1); PG8_SCHED; PG8_LDA(At, 0, 0); PG8_STAGE(PG8_SA(1, 1), a1 + hstepA, voffA);
;             PG8_WAIT_V(8); PG8_WAIT_L(0); PG8_BAR; PG8_MMA(0, 0, At, B0); PG8_MMA(0, 1, At, B1); PG8_BAR; PG8_SCHED;
;             PG8_LDA(At, 0, 1); PG8_STAGE(PG8_SB(0, 0), b2, voffB); PG8_STAGE(PG8_SB(0, 1), b2 + hstepB, voffB); PG8_STAGE(PG8_SA(0, 0), a2, voffA);
;             PG8_WAIT_V(8); PG8_WAIT_L(0); PG8_BAR; PG8_MMA(1, 0, At, B0); PG8_MMA(1, 1, At, B1); PG8_BAR; PG8_SCHED;
.LBB0_655:
	ds_read_b128 v[152:155], v149
	ds_read_b128 v[156:159], v149 offset:1024
	ds_read_b128 v[160:163], v149 offset:2048
	ds_read_b128 v[164:167], v149 offset:3072
	ds_read_b128 v[168:171], v150
	ds_read_b128 v[172:175], v150 offset:1024
	ds_read_b128 v[176:179], v150 offset:2048
	ds_read_b128 v[184:187], v150 offset:3072
	s_add_u32 s26, s24, 0xfffe0080
	s_addc_u32 s27, s25, -1
	s_cmp_eq_u32 s51, 4
	s_cselect_b32 s29, s13, s27
	s_cselect_b32 s28, s47, s26
	s_cselect_b32 s27, s11, s50
	s_cselect_b32 s26, s48, s49
	v_lshl_add_u64 v[144:145], s[24:25], 0, v[136:137]
	s_add_i32 m0, s19, 0xc000
	ds_read_b128 v[188:191], v151
	ds_read_b128 v[192:195], v151 offset:1024
	ds_read_b128 v[196:199], v151 offset:2048
	ds_read_b128 v[200:203], v151 offset:3072
	ds_read_b128 v[204:207], v151 offset:4096
	ds_read_b128 v[208:211], v151 offset:5120
	ds_read_b128 v[212:215], v151 offset:6144
	ds_read_b128 v[216:219], v151 offset:7168
	global_load_lds_dwordx4 v[144:145], off
	v_lshl_add_u64 v[144:145], s[24:25], 0, v[138:139]
	s_add_i32 m0, s19, 0xe000
	s_nop 0
	global_load_lds_dwordx4 v[144:145], off
	s_waitcnt vmcnt(8)
	s_waitcnt lgkmcnt(0)
	s_barrier
	s_setprio 1
	s_waitcnt lgkmcnt(0)
	v_mfma_f32_16x16x32_bf16 v[120:123], v[152:155], v[188:191], v[120:123]
	v_mfma_f32_16x16x32_bf16 v[124:127], v[160:163], v[188:191], v[124:127]
	v_mfma_f32_16x16x32_bf16 v[104:107], v[152:155], v[196:199], v[104:107]
	v_mfma_f32_16x16x32_bf16 v[108:111], v[160:163], v[196:199], v[108:111]
	v_mfma_f32_16x16x32_bf16 v[88:91], v[152:155], v[204:207], v[88:91]
	v_mfma_f32_16x16x32_bf16 v[92:95], v[160:163], v[204:207], v[92:95]
	v_mfma_f32_16x16x32_bf16 v[72:75], v[152:155], v[212:215], v[72:75]
	v_mfma_f32_16x16x32_bf16 v[76:79], v[160:163], v[212:215], v[76:79]
	v_mfma_f32_16x16x32_bf16 v[120:123], v[156:159], v[192:195], v[120:123]
	v_mfma_f32_16x16x32_bf16 v[124:127], v[164:167], v[192:195], v[124:127]
	v_mfma_f32_16x16x32_bf16 v[104:107], v[156:159], v[200:203], v[104:107]
	v_mfma_f32_16x16x32_bf16 v[108:111], v[164:167], v[200:203], v[108:111]
	v_mfma_f32_16x16x32_bf16 v[88:91], v[156:159], v[208:211], v[88:91]
	v_mfma_f32_16x16x32_bf16 v[92:95], v[164:167], v[208:211], v[92:95]
	v_mfma_f32_16x16x32_bf16 v[72:75], v[156:159], v[216:219], v[72:75]
	v_mfma_f32_16x16x32_bf16 v[76:79], v[164:167], v[216:219], v[76:79]
	s_setprio 0
	s_setprio 1
	v_mfma_f32_16x16x32_bf16 v[112:115], v[168:171], v[188:191], v[112:115]
	v_mfma_f32_16x16x32_bf16 v[116:119], v[176:179], v[188:191], v[116:119]
	v_mfma_f32_16x16x32_bf16 v[96:99], v[168:171], v[196:199], v[96:99]
	v_mfma_f32_16x16x32_bf16 v[100:103], v[176:179], v[196:199], v[100:103]
	v_mfma_f32_16x16x32_bf16 v[80:83], v[168:171], v[204:207], v[80:83]
	v_mfma_f32_16x16x32_bf16 v[84:87], v[176:179], v[204:207], v[84:87]
	v_mfma_f32_16x16x32_bf16 v[64:67], v[168:171], v[212:215], v[64:67]
	v_mfma_f32_16x16x32_bf16 v[68:71], v[176:179], v[212:215], v[68:71]
	v_mfma_f32_16x16x32_bf16 v[112:115], v[172:175], v[192:195], v[112:115]
	v_mfma_f32_16x16x32_bf16 v[116:119], v[184:187], v[192:195], v[116:119]
	v_mfma_f32_16x16x32_bf16 v[96:99], v[172:175], v[200:203], v[96:99]
	v_mfma_f32_16x16x32_bf16 v[100:103], v[184:187], v[200:203], v[100:103]
	v_mfma_f32_16x16x32_bf16 v[80:83], v[172:175], v[208:211], v[80:83]
	v_mfma_f32_16x16x32_bf16 v[84:87], v[184:187], v[208:211], v[84:87]
	v_mfma_f32_16x16x32_bf16 v[64:67], v[172:175], v[216:219], v[64:67]
	v_mfma_f32_16x16x32_bf16 v[68:71], v[184:187], v[216:219], v[68:71]
	s_setprio 0
	s_barrier
	s_add_i32 s52, s44, s34
	v_lshl_add_u64 v[144:145], s[26:27], 0, v[130:131]
	s_mov_b32 m0, s52
	ds_read_b128 v[188:191], v151 offset:16384
	ds_read_b128 v[192:195], v151 offset:17408
	ds_read_b128 v[196:199], v151 offset:18432
	ds_read_b128 v[200:203], v151 offset:19456
	ds_read_b128 v[204:207], v151 offset:20480
	ds_read_b128 v[208:211], v151 offset:21504
	ds_read_b128 v[212:215], v151 offset:22528
	ds_read_b128 v[216:219], v151 offset:23552
	global_load_lds_dwordx4 v[144:145], off
	s_add_i32 m0, s52, 0x2000
	s_add_u32 s52, s26, 0x20000
	v_lshl_add_u64 v[180:181], s[26:27], 0, v[134:135]
	s_addc_u32 s53, s27, 0
	s_add_i32 s55, s45, s34
	global_load_lds_dwordx4 v[180:181], off
	v_lshl_add_u64 v[182:183], s[52:53], 0, v[130:131]
	s_mov_b32 m0, s55
	v_lshl_add_u64 v[220:221], s[28:29], 0, v[132:133]
	global_load_lds_dwordx4 v[182:183], off
	v_lshl_add_u64 v[182:183], s[52:53], 0, v[134:135]
	s_add_i32 m0, s55, 0x2000
	s_nop 0
	global_load_lds_dwordx4 v[182:183], off
	v_lshl_add_u64 v[182:183], s[28:29], 0, v[128:129]
	s_mov_b32 m0, s19
	s_nop 0
	global_load_lds_dwordx4 v[182:183], off
	s_mov_b32 m0, s35
	s_nop 0
	global_load_lds_dwordx4 v[220:221], off
	s_waitcnt vmcnt(8)
	s_waitcnt lgkmcnt(0)
	s_barrier
; #define PG8_STAGE(bufoff, gbase, voff) do { _Pragma("unroll") for (int _i = 0; _i < 2; ++_i) \
;         __builtin_amdgcn_global_load_lds((const unsigned*)((const char*)(gbase) + (voff)[_i]), (PG8_LAS unsigned*)(lds + (bufoff) + ldsw + _i * 8192), 16, 0, 0); } while (0)
; #define PG8_LDA(dst, b, h) do { _Pragma("unroll") for (int m = 0; m < 4; ++m) _Pragma("unroll") for (int k = 0; k < 2; ++k) dst[m][k] = *(const PG8_LAS bf16x8*)(lds + PG8_SA(b, h) + aoff + m * 2048 + k * 1024); } while (0)
; #define PG8_LDB(dst, b, h) do { _Pragma("unroll") for (int n = 0; n < 2; ++n) _Pragma("unroll") for (int k = 0; k < 2; ++k) dst[n][k] = *(const PG8_LAS bf16x8*)(lds + PG8_SB(b, h) + boff + n * 2048 + k * 1024); } while (0)
; #define PG8_MMA(ai, bj, At, Bt) do { __builtin_amdgcn_s_setprio(1); _Pragma("unroll") for (int m = 0; m < 4; ++m) _Pragma("unroll") for (int n = 0; n < 2; ++n) _Pragma("unroll") for (int k = 0; k < 2; ++k) \
;         acc[ai][bj][m][n] = __builtin_amdgcn_mfma_f32_16x16x32_bf16(Bt[n][k], At[m][k], acc[ai][bj][m][n], 0, 0, 0); __builtin_amdgcn_s_setprio(0); } while (0)
; #define PG8_WAIT_V(n) asm volatile("s_waitcnt vmcnt(" #n ")" ::: "memory")
; #define PG8_WAIT_L(n) asm volatile("s_waitcnt lgkmcnt(" #n ")" ::: "memory")
; #define PG8_BAR __builtin_amdgcn_s_barrier()
; #define PG8_SCHED __builtin_amdgcn_sched_barrier(0)
; template <class Epi>
; DI void gemm_phase(PG8_LAS unsigned char* lds, const Gemm g, const StaticOrder& S, const Epi& E) {
;     ...
;             PG8_WAIT_V(8); PG8_WAIT_L(0); PG8_BAR; PG8_MMA(1, 0, At, B0); PG8_MMA(1, 1, At, B1); PG8_BAR; PG8_SCHED;
;             PG8_LDB(B0, 1, 0); PG8_LDB(B1, 1, 1); PG8_SCHED; PG8_LDA(At, 1, 0); PG8_STAGE(PG8_SA(0, 1), a2 + hstepA, voffA);
;             PG8_WAIT_V(8); PG8_WAIT_L(0); PG8_BAR; PG8_MMA(0, 0, At, B0); PG8_MMA(0, 1, At, B1); PG8_BAR; PG8_SCHED;
	s_setprio 1
	s_waitcnt lgkmcnt(0)
	v_mfma_f32_16x16x32_bf16 v[56:59], v[152:155], v[188:191], v[56:59]
	v_mfma_f32_16x16x32_bf16 v[60:63], v[160:163], v[188:191], v[60:63]
	v_mfma_f32_16x16x32_bf16 v[40:43], v[152:155], v[196:199], v[40:43]
	v_mfma_f32_16x16x32_bf16 v[44:47], v[160:163], v[196:199], v[44:47]
	v_mfma_f32_16x16x32_bf16 v[24:27], v[152:155], v[204:207], v[24:27]
	v_mfma_f32_16x16x32_bf16 v[28:31], v[160:163], v[204:207], v[28:31]
	v_mfma_f32_16x16x32_bf16 v[8:11], v[152:155], v[212:215], v[8:11]
	v_mfma_f32_16x16x32_bf16 v[12:15], v[160:163], v[212:215], v[12:15]
	v_mfma_f32_16x16x32_bf16 v[56:59], v[156:159], v[192:195], v[56:59]
	v_mfma_f32_16x16x32_bf16 v[60:63], v[164:167], v[192:195], v[60:63]
	v_mfma_f32_16x16x32_bf16 v[40:43], v[156:159], v[200:203], v[40:43]
	v_mfma_f32_16x16x32_bf16 v[44:47], v[164:167], v[200:203], v[44:47]
	v_mfma_f32_16x16x32_bf16 v[24:27], v[156:159], v[208:211], v[24:27]
	v_mfma_f32_16x16x32_bf16 v[28:31], v[164:167], v[208:211], v[28:31]
	v_mfma_f32_16x16x32_bf16 v[8:11], v[156:159], v[216:219], v[8:11]
	v_mfma_f32_16x16x32_bf16 v[12:15], v[164:167], v[216:219], v[12:15]
	s_setprio 0
	s_setprio 1
	v_mfma_f32_16x16x32_bf16 v[48:51], v[168:171], v[188:191], v[48:51]
	v_mfma_f32_16x16x32_bf16 v[52:55], v[176:179], v[188:191], v[52:55]
	v_mfma_f32_16x16x32_bf16 v[32:35], v[168:171], v[196:199], v[32:35]
	v_mfma_f32_16x16x32_bf16 v[36:39], v[176:179], v[196:199], v[36:39]
	v_mfma_f32_16x16x32_bf16 v[16:19], v[168:171], v[204:207], v[16:19]
	v_mfma_f32_16x16x32_bf16 v[20:23], v[176:179], v[204:207], v[20:23]
	v_mfma_f32_16x16x32_bf16 v[0:3], v[168:171], v[212:215], v[0:3]
	v_mfma_f32_16x16x32_bf16 v[4:7], v[176:179], v[212:215], v[4:7]
	v_mfma_f32_16x16x32_bf16 v[48:51], v[172:175], v[192:195], v[48:51]
	v_mfma_f32_16x16x32_bf16 v[52:55], v[184:187], v[192:195], v[52:55]
	v_mfma_f32_16x16x32_bf16 v[32:35], v[172:175], v[200:203], v[32:35]
	v_mfma_f32_16x16x32_bf16 v[36:39], v[184:187], v[200:203], v[36:39]
	v_mfma_f32_16x16x32_bf16 v[16:19], v[172:175], v[208:211], v[16:19]
	v_mfma_f32_16x16x32_bf16 v[20:23], v[184:187], v[208:211], v[20:23]
	v_mfma_f32_16x16x32_bf16 v[0:3], v[172:175], v[216:219], v[0:3]
	v_mfma_f32_16x16x32_bf16 v[4:7], v[184:187], v[216:219], v[4:7]
	s_setprio 0
	s_barrier
	s_add_i32 s52, 16, 0x18000
	s_add_i32 s53, 16, 0x1c000
	v_add_u32_e32 v164, s52, v148
	v_add_u32_e32 v184, s53, v148
	ds_read_b128 v[152:155], v164
	ds_read_b128 v[156:159], v164 offset:1024
	ds_read_b128 v[160:163], v164 offset:2048
	ds_read_b128 v[164:167], v164 offset:3072
	ds_read_b128 v[168:171], v184
	ds_read_b128 v[172:175], v184 offset:1024
	ds_read_b128 v[176:179], v184 offset:2048
	ds_read_b128 v[184:187], v184 offset:3072
	s_add_u32 s28, s28, 0x20000
	s_addc_u32 s29, s29, 0
	s_mov_b32 m0, s36
	v_lshl_add_u64 v[222:223], s[28:29], 0, v[128:129]
	ds_read_b128 v[188:191], v151 offset:32768
	ds_read_b128 v[192:195], v151 offset:33792
	ds_read_b128 v[196:199], v151 offset:34816
	ds_read_b128 v[200:203], v151 offset:35840
	ds_read_b128 v[204:207], v151 offset:36864
	ds_read_b128 v[208:211], v151 offset:37888
	ds_read_b128 v[212:215], v151 offset:38912
	ds_read_b128 v[216:219], v151 offset:39936
	global_load_lds_dwordx4 v[222:223], off
	v_lshl_add_u64 v[222:223], s[28:29], 0, v[132:133]
	s_mov_b32 m0, s37
	s_nop 0
	global_load_lds_dwordx4 v[222:223], off
	s_waitcnt vmcnt(8)
	s_waitcnt lgkmcnt(0)
	s_barrier
	s_setprio 1
	s_waitcnt lgkmcnt(0)
	v_mfma_f32_16x16x32_bf16 v[120:123], v[152:155], v[188:191], v[120:123]
	v_mfma_f32_16x16x32_bf16 v[124:127], v[160:163], v[188:191], v[124:127]
	v_mfma_f32_16x16x32_bf16 v[104:107], v[152:155], v[196:199], v[104:107]
	v_mfma_f32_16x16x32_bf16 v[108:111], v[160:163], v[196:199], v[108:111]
	v_mfma_f32_16x16x32_bf16 v[88:91], v[152:155], v[204:207], v[88:91]
	v_mfma_f32_16x16x32_bf16 v[92:95], v[160:163], v[204:207], v[92:95]
	v_mfma_f32_16x16x32_bf16 v[72:75], v[152:155], v[212:215], v[72:75]
	v_mfma_f32_16x16x32_bf16 v[76:79], v[160:163], v[212:215], v[76:79]
	v_mfma_f32_16x16x32_bf16 v[120:123], v[156:159], v[192:195], v[120:123]
	v_mfma_f32_16x16x32_bf16 v[124:127], v[164:167], v[192:195], v[124:127]
	v_mfma_f32_16x16x32_bf16 v[104:107], v[156:159], v[200:203], v[104:107]
	v_mfma_f32_16x16x32_bf16 v[108:111], v[164:167], v[200:203], v[108:111]
	v_mfma_f32_16x16x32_bf16 v[88:91], v[156:159], v[208:211], v[88:91]
	v_mfma_f32_16x16x32_bf16 v[92:95], v[164:167], v[208:211], v[92:95]
	v_mfma_f32_16x16x32_bf16 v[72:75], v[156:159], v[216:219], v[72:75]
	v_mfma_f32_16x16x32_bf16 v[76:79], v[164:167], v[216:219], v[76:79]
	s_setprio 0
	s_setprio 1
	v_mfma_f32_16x16x32_bf16 v[112:115], v[168:171], v[188:191], v[112:115]
	v_mfma_f32_16x16x32_bf16 v[116:119], v[176:179], v[188:191], v[116:119]
	v_mfma_f32_16x16x32_bf16 v[96:99], v[168:171], v[196:199], v[96:99]
	v_mfma_f32_16x16x32_bf16 v[100:103], v[176:179], v[196:199], v[100:103]
	v_mfma_f32_16x16x32_bf16 v[80:83], v[168:171], v[204:207], v[80:83]
	v_mfma_f32_16x16x32_bf16 v[84:87], v[176:179], v[204:207], v[84:87]
	v_mfma_f32_16x16x32_bf16 v[64:67], v[168:171], v[212:215], v[64:67]
	v_mfma_f32_16x16x32_bf16 v[68:71], v[176:179], v[212:215], v[68:71]
	v_mfma_f32_16x16x32_bf16 v[112:115], v[172:175], v[192:195], v[112:115]
	v_mfma_f32_16x16x32_bf16 v[116:119], v[184:187], v[192:195], v[116:119]
	v_mfma_f32_16x16x32_bf16 v[96:99], v[172:175], v[200:203], v[96:99]
	v_mfma_f32_16x16x32_bf16 v[100:103], v[184:187], v[200:203], v[100:103]
	v_mfma_f32_16x16x32_bf16 v[80:83], v[172:175], v[208:211], v[80:83]
	v_mfma_f32_16x16x32_bf16 v[84:87], v[184:187], v[208:211], v[84:87]
	v_mfma_f32_16x16x32_bf16 v[64:67], v[172:175], v[216:219], v[64:67]
	v_mfma_f32_16x16x32_bf16 v[68:71], v[184:187], v[216:219], v[68:71]
	s_setprio 0
	s_barrier
; #define PG8_STAGE(bufoff, gbase, voff) do { _Pragma("unroll") for (int _i = 0; _i < 2; ++_i) \
;         __builtin_amdgcn_global_load_lds((const unsigned*)((const char*)(gbase) + (voff)[_i]), (PG8_LAS unsigned*)(lds + (bufoff) + ldsw + _i * 8192), 16, 0, 0); } while (0)
; #define PG8_LDA(dst, b, h) do { _Pragma("unroll") for (int m = 0; m < 4; ++m) _Pragma("unroll") for (int k = 0; k < 2; ++k) dst[m][k] = *(const PG8_LAS bf16x8*)(lds + PG8_SA(b, h) + aoff + m * 2048 + k * 1024); } while (0)
; #define PG8_MMA(ai, bj, At, Bt) do { __builtin_amdgcn_s_setprio(1); _Pragma("unroll") for (int m = 0; m < 4; ++m) _Pragma("unroll") for (int n = 0; n < 2; ++n) _Pragma("unroll") for (int k = 0; k < 2; ++k) \
;         acc[ai][bj][m][n] = __builtin_amdgcn_mfma_f32_16x16x32_bf16(Bt[n][k], At[m][k], acc[ai][bj][m][n], 0, 0, 0); __builtin_amdgcn_s_setprio(0); } while (0)
; #define PG8_WAIT_V(n) asm volatile("s_waitcnt vmcnt(" #n ")" ::: "memory")
; #define PG8_WAIT_L(n) asm volatile("s_waitcnt lgkmcnt(" #n ")" ::: "memory")
; #define PG8_BAR __builtin_amdgcn_s_barrier()
; #define PG8_SCHED __builtin_amdgcn_sched_barrier(0)
; template <class Epi>
; DI void gemm_phase(PG8_LAS unsigned char* lds, const Gemm g, const StaticOrder& S, const Epi& E) {
;     ...
;             PG8_LDA(At, 1, 1); PG8_STAGE(PG8_SB(1, 0), b3, voffB); PG8_STAGE(PG8_SB(1, 1), b3 + hstepB, voffB); PG8_STAGE(PG8_SA(1, 0), a3, voffA);
;             PG8_WAIT_V(8); PG8_WAIT_L(0); PG8_BAR; PG8_MMA(1, 0, At, B0); PG8_MMA(1, 1, At, B1); PG8_BAR; PG8_SCHED;
;         }
;         if (wr == 0) PG8_BAR;
	s_add_i32 s28, s52, s34
	v_lshl_add_u64 v[144:145], v[144:145], 0, s[6:7]
	s_mov_b32 m0, s28
	ds_read_b128 v[188:191], v151 offset:49152
	ds_read_b128 v[192:195], v151 offset:50176
	ds_read_b128 v[196:199], v151 offset:51200
	ds_read_b128 v[200:203], v151 offset:52224
	ds_read_b128 v[204:207], v151 offset:53248
	ds_read_b128 v[208:211], v151 offset:54272
	ds_read_b128 v[212:215], v151 offset:55296
	ds_read_b128 v[216:219], v151 offset:56320
	global_load_lds_dwordx4 v[144:145], off
	s_add_i32 m0, s28, 0x2000
	s_add_u32 s26, s26, 0x20080
	v_lshl_add_u64 v[144:145], v[180:181], 0, s[6:7]
	s_addc_u32 s27, s27, 0
	s_add_i32 s28, s53, s34
	global_load_lds_dwordx4 v[144:145], off
	v_lshl_add_u64 v[144:145], s[26:27], 0, v[130:131]
	s_mov_b32 m0, s28
	s_nop 0
	global_load_lds_dwordx4 v[144:145], off
	v_lshl_add_u64 v[144:145], s[26:27], 0, v[134:135]
	s_add_i32 m0, s28, 0x2000
	s_nop 0
	global_load_lds_dwordx4 v[144:145], off
	v_lshl_add_u64 v[144:145], v[182:183], 0, s[6:7]
	s_mov_b32 m0, s40
	s_nop 0
	global_load_lds_dwordx4 v[144:145], off
	v_lshl_add_u64 v[144:145], v[220:221], 0, s[6:7]
	s_mov_b32 m0, s41
	s_nop 0
	global_load_lds_dwordx4 v[144:145], off
	s_waitcnt vmcnt(8)
	s_waitcnt lgkmcnt(0)
	s_barrier
	s_setprio 1
	s_waitcnt lgkmcnt(0)
	v_mfma_f32_16x16x32_bf16 v[56:59], v[152:155], v[188:191], v[56:59]
	v_mfma_f32_16x16x32_bf16 v[60:63], v[160:163], v[188:191], v[60:63]
	v_mfma_f32_16x16x32_bf16 v[40:43], v[152:155], v[196:199], v[40:43]
	v_mfma_f32_16x16x32_bf16 v[44:47], v[160:163], v[196:199], v[44:47]
	v_mfma_f32_16x16x32_bf16 v[24:27], v[152:155], v[204:207], v[24:27]
	v_mfma_f32_16x16x32_bf16 v[28:31], v[160:163], v[204:207], v[28:31]
	v_mfma_f32_16x16x32_bf16 v[8:11], v[152:155], v[212:215], v[8:11]
	v_mfma_f32_16x16x32_bf16 v[12:15], v[160:163], v[212:215], v[12:15]
	v_mfma_f32_16x16x32_bf16 v[56:59], v[156:159], v[192:195], v[56:59]
	v_mfma_f32_16x16x32_bf16 v[60:63], v[164:167], v[192:195], v[60:63]
	v_mfma_f32_16x16x32_bf16 v[40:43], v[156:159], v[200:203], v[40:43]
	v_mfma_f32_16x16x32_bf16 v[44:47], v[164:167], v[200:203], v[44:47]
	v_mfma_f32_16x16x32_bf16 v[24:27], v[156:159], v[208:211], v[24:27]
	v_mfma_f32_16x16x32_bf16 v[28:31], v[164:167], v[208:211], v[28:31]
	v_mfma_f32_16x16x32_bf16 v[8:11], v[156:159], v[216:219], v[8:11]
	v_mfma_f32_16x16x32_bf16 v[12:15], v[164:167], v[216:219], v[12:15]
	s_setprio 0
	s_setprio 1
	v_mfma_f32_16x16x32_bf16 v[48:51], v[168:171], v[188:191], v[48:51]
	v_mfma_f32_16x16x32_bf16 v[52:55], v[176:179], v[188:191], v[52:55]
	v_mfma_f32_16x16x32_bf16 v[32:35], v[168:171], v[196:199], v[32:35]
	v_mfma_f32_16x16x32_bf16 v[36:39], v[176:179], v[196:199], v[36:39]
	v_mfma_f32_16x16x32_bf16 v[16:19], v[168:171], v[204:207], v[16:19]
	v_mfma_f32_16x16x32_bf16 v[20:23], v[176:179], v[204:207], v[20:23]
	v_mfma_f32_16x16x32_bf16 v[0:3], v[168:171], v[212:215], v[0:3]
	v_mfma_f32_16x16x32_bf16 v[4:7], v[176:179], v[212:215], v[4:7]
	v_mfma_f32_16x16x32_bf16 v[48:51], v[172:175], v[192:195], v[48:51]
	v_mfma_f32_16x16x32_bf16 v[52:55], v[184:187], v[192:195], v[52:55]
	v_mfma_f32_16x16x32_bf16 v[32:35], v[172:175], v[200:203], v[32:35]
	v_mfma_f32_16x16x32_bf16 v[36:39], v[184:187], v[200:203], v[36:39]
	v_mfma_f32_16x16x32_bf16 v[16:19], v[172:175], v[208:211], v[16:19]
	v_mfma_f32_16x16x32_bf16 v[20:23], v[184:187], v[208:211], v[20:23]
	v_mfma_f32_16x16x32_bf16 v[0:3], v[172:175], v[216:219], v[0:3]
	v_mfma_f32_16x16x32_bf16 v[4:7], v[184:187], v[216:219], v[4:7]
	s_setprio 0
	s_add_i32 s51, s51, 2
	s_add_u32 s24, s24, 0x100
	s_addc_u32 s25, s25, 0
	s_add_u32 s49, s49, 0x100
	s_addc_u32 s50, s50, 0
	s_cmp_gt_u32 s51, 5
	s_barrier
	s_cbranch_scc0 .LBB0_655
	s_and_b64 vcc, exec, s[8:9]
	s_cbranch_vccz .LBB0_658
	s_barrier

; #define PG8_STAGE(bufoff, gbase, voff) do { _Pragma("unroll") for (int _i = 0; _i < 2; ++_i) \
;         __builtin_amdgcn_global_load_lds((const unsigned*)((const char*)(gbase) + (voff)[_i]), (PG8_LAS unsigned*)(lds + (bufoff) + ldsw + _i * 8192), 16, 0, 0); } while (0)
; #define PG8_LDA(dst, b, h) do { _Pragma("unroll") for (int m = 0; m < 4; ++m) _Pragma("unroll") for (int k = 0; k < 2; ++k) dst[m][k] = *(const PG8_LAS bf16x8*)(lds + PG8_SA(b, h) + aoff + m * 2048 + k * 1024); } while (0)
; #define PG8_LDB(dst, b, h) do { _Pragma("unroll") for (int n = 0; n < 2; ++n) _Pragma("unroll") for (int k = 0; k < 2; ++k) dst[n][k] = *(const PG8_LAS bf16x8*)(lds + PG8_SB(b, h) + boff + n * 2048 + k * 1024); } while (0)
; #define PG8_MMA(ai, bj, At, Bt) do { __builtin_amdgcn_s_setprio(1); _Pragma("unroll") for (int m = 0; m < 4; ++m) _Pragma("unroll") for (int n = 0; n < 2; ++n) _Pragma("unroll") for (int k = 0; k < 2; ++k) \
;         acc[ai][bj][m][n] = __builtin_amdgcn_mfma_f32_16x16x32_bf16(Bt[n][k], At[m][k], acc[ai][bj][m][n], 0, 0, 0); __builtin_amdgcn_s_setprio(0); } while (0)
; #define PG8_WAIT_V(n) asm volatile("s_waitcnt vmcnt(" #n ")" ::: "memory")
; #define PG8_WAIT_L(n) asm volatile("s_waitcnt lgkmcnt(" #n ")" ::: "memory")
; #define PG8_BAR __builtin_amdgcn_s_barrier()
; #define PG8_SCHED __builtin_amdgcn_sched_barrier(0)
; template <class Epi>
; DI void gemm_phase(PG8_LAS unsigned char* lds, const Gemm g, const StaticOrder& S, const Epi& E) {
;     ...
;         for (int t = 0; t < nt; t += 2) {
;             const bool last = (t == nt - 2);
;             const char* a1 = cA + (size_t)(t + 1) * kstep;
;             const char* a2 = last ? nA : cA + (size_t)(t + 2) * kstep; const char* b2 = last ? nB : cB + (size_t)(t + 2) * kstep;
;             const char* a3 = a2 + kstep; const char* b3 = b2 + kstep;
;             PG8_LDB(B0, 0, 0); PG8_LDB(B1, 0, 1); PG8_SCHED; PG8_LDA(At, 0, 0); PG8_STAGE(PG8_SA(1, 1), a1 + hstepA, voffA);
;             PG8_WAIT_V(8); PG8_WAIT_L(0); PG8_BAR; PG8_MMA(0, 0, At, B0); PG8_MMA(0, 1, At, B1); PG8_BAR; PG8_SCHED;
;             PG8_LDA(At, 0, 1); PG8_STAGE(PG8_SB(0, 0), b2, voffB); PG8_STAGE(PG8_SB(0, 1), b2 + hstepB, voffB); PG8_STAGE(PG8_SA(0, 0), a2, voffA);
;             PG8_WAIT_V(8); PG8_WAIT_L(0); PG8_BAR; PG8_MMA(1, 0, At, B0); PG8_MMA(1, 1, At, B1); PG8_BAR; PG8_SCHED;
.LBB0_852:
	ds_read_b128 v[144:147], v155
	ds_read_b128 v[148:151], v155 offset:1024
	ds_read_b128 v[158:161], v155 offset:2048
	ds_read_b128 v[162:165], v155 offset:3072
	ds_read_b128 v[166:169], v156
	ds_read_b128 v[170:173], v156 offset:1024
	ds_read_b128 v[174:177], v156 offset:2048
	ds_read_b128 v[178:181], v156 offset:3072
	s_add_u32 s30, s28, 0xfffc0080
	s_addc_u32 s31, s29, -1
	s_cmp_eq_u32 s91, 12
	s_cselect_b32 s35, s21, s31
	s_cselect_b32 s34, s85, s30
	s_cselect_b32 s31, s19, s90
	s_cselect_b32 s30, s86, s87
	v_lshl_add_u64 v[214:215], s[28:29], 0, v[136:137]
	s_add_i32 m0, s27, 0xc000
	ds_read_b128 v[182:185], v157
	ds_read_b128 v[186:189], v157 offset:1024
	ds_read_b128 v[190:193], v157 offset:2048
	ds_read_b128 v[194:197], v157 offset:3072
	ds_read_b128 v[198:201], v157 offset:4096
	ds_read_b128 v[202:205], v157 offset:5120
	ds_read_b128 v[206:209], v157 offset:6144
	ds_read_b128 v[210:213], v157 offset:7168
	global_load_lds_dwordx4 v[214:215], off
	v_lshl_add_u64 v[214:215], s[28:29], 0, v[138:139]
	s_add_i32 m0, s27, 0xe000
	s_nop 0
	global_load_lds_dwordx4 v[214:215], off
	s_waitcnt vmcnt(8)
	s_waitcnt lgkmcnt(0)
	s_barrier
	s_setprio 1
	s_waitcnt lgkmcnt(0)
	v_mfma_f32_16x16x32_bf16 v[124:127], v[144:147], v[182:185], v[124:127]
	v_mfma_f32_16x16x32_bf16 v[120:123], v[158:161], v[182:185], v[120:123]
	v_mfma_f32_16x16x32_bf16 v[108:111], v[144:147], v[190:193], v[108:111]
	v_mfma_f32_16x16x32_bf16 v[104:107], v[158:161], v[190:193], v[104:107]
	v_mfma_f32_16x16x32_bf16 v[92:95], v[144:147], v[198:201], v[92:95]
	v_mfma_f32_16x16x32_bf16 v[88:91], v[158:161], v[198:201], v[88:91]
	v_mfma_f32_16x16x32_bf16 v[76:79], v[144:147], v[206:209], v[76:79]
	v_mfma_f32_16x16x32_bf16 v[72:75], v[158:161], v[206:209], v[72:75]
	v_mfma_f32_16x16x32_bf16 v[124:127], v[148:151], v[186:189], v[124:127]
	v_mfma_f32_16x16x32_bf16 v[120:123], v[162:165], v[186:189], v[120:123]
	v_mfma_f32_16x16x32_bf16 v[108:111], v[148:151], v[194:197], v[108:111]
	v_mfma_f32_16x16x32_bf16 v[104:107], v[162:165], v[194:197], v[104:107]
	v_mfma_f32_16x16x32_bf16 v[92:95], v[148:151], v[202:205], v[92:95]
	v_mfma_f32_16x16x32_bf16 v[88:91], v[162:165], v[202:205], v[88:91]
	v_mfma_f32_16x16x32_bf16 v[76:79], v[148:151], v[210:213], v[76:79]
	v_mfma_f32_16x16x32_bf16 v[72:75], v[162:165], v[210:213], v[72:75]
	s_setprio 0
	s_setprio 1
	v_mfma_f32_16x16x32_bf16 v[116:119], v[166:169], v[182:185], v[116:119]
	v_mfma_f32_16x16x32_bf16 v[112:115], v[174:177], v[182:185], v[112:115]
	v_mfma_f32_16x16x32_bf16 v[100:103], v[166:169], v[190:193], v[100:103]
	v_mfma_f32_16x16x32_bf16 v[96:99], v[174:177], v[190:193], v[96:99]
	v_mfma_f32_16x16x32_bf16 v[84:87], v[166:169], v[198:201], v[84:87]
	v_mfma_f32_16x16x32_bf16 v[80:83], v[174:177], v[198:201], v[80:83]
	v_mfma_f32_16x16x32_bf16 v[68:71], v[166:169], v[206:209], v[68:71]
	v_mfma_f32_16x16x32_bf16 v[64:67], v[174:177], v[206:209], v[64:67]
	v_mfma_f32_16x16x32_bf16 v[116:119], v[170:173], v[186:189], v[116:119]
	v_mfma_f32_16x16x32_bf16 v[112:115], v[178:181], v[186:189], v[112:115]
	v_mfma_f32_16x16x32_bf16 v[100:103], v[170:173], v[194:197], v[100:103]
	v_mfma_f32_16x16x32_bf16 v[96:99], v[178:181], v[194:197], v[96:99]
	v_mfma_f32_16x16x32_bf16 v[84:87], v[170:173], v[202:205], v[84:87]
	v_mfma_f32_16x16x32_bf16 v[80:83], v[178:181], v[202:205], v[80:83]
	v_mfma_f32_16x16x32_bf16 v[68:71], v[170:173], v[210:213], v[68:71]
	v_mfma_f32_16x16x32_bf16 v[64:67], v[178:181], v[210:213], v[64:67]
	s_setprio 0
	s_barrier
	s_add_i32 s88, s50, s38
	v_lshl_add_u64 v[214:215], s[30:31], 0, v[130:131]
	s_mov_b32 m0, s88
	ds_read_b128 v[182:185], v157 offset:16384
	ds_read_b128 v[186:189], v157 offset:17408
	ds_read_b128 v[190:193], v157 offset:18432
	ds_read_b128 v[194:197], v157 offset:19456
	ds_read_b128 v[198:201], v157 offset:20480
	ds_read_b128 v[202:205], v157 offset:21504
	ds_read_b128 v[206:209], v157 offset:22528
	ds_read_b128 v[210:213], v157 offset:23552
	global_load_lds_dwordx4 v[214:215], off
	s_add_i32 m0, s88, 0x2000
	s_add_u32 s92, s30, 0x40000
	v_lshl_add_u64 v[216:217], s[30:31], 0, v[134:135]
	s_addc_u32 s93, s31, 0
	s_add_i32 s88, s51, s38
	global_load_lds_dwordx4 v[216:217], off
	v_lshl_add_u64 v[218:219], s[92:93], 0, v[130:131]
	s_mov_b32 m0, s88
	v_lshl_add_u64 v[220:221], s[34:35], 0, v[132:133]
	global_load_lds_dwordx4 v[218:219], off
	v_lshl_add_u64 v[218:219], s[92:93], 0, v[134:135]
	s_add_i32 m0, s88, 0x2000
	s_nop 0
	global_load_lds_dwordx4 v[218:219], off
	v_lshl_add_u64 v[218:219], s[34:35], 0, v[128:129]
	s_mov_b32 m0, s27
	s_nop 0
	global_load_lds_dwordx4 v[218:219], off
	s_mov_b32 m0, s39
	s_nop 0
	global_load_lds_dwordx4 v[220:221], off
	s_waitcnt vmcnt(8)
	s_waitcnt lgkmcnt(0)
	s_barrier
; #define PG8_STAGE(bufoff, gbase, voff) do { _Pragma("unroll") for (int _i = 0; _i < 2; ++_i) \
;         __builtin_amdgcn_global_load_lds((const unsigned*)((const char*)(gbase) + (voff)[_i]), (PG8_LAS unsigned*)(lds + (bufoff) + ldsw + _i * 8192), 16, 0, 0); } while (0)
; #define PG8_LDA(dst, b, h) do { _Pragma("unroll") for (int m = 0; m < 4; ++m) _Pragma("unroll") for (int k = 0; k < 2; ++k) dst[m][k] = *(const PG8_LAS bf16x8*)(lds + PG8_SA(b, h) + aoff + m * 2048 + k * 1024); } while (0)
; #define PG8_LDB(dst, b, h) do { _Pragma("unroll") for (int n = 0; n < 2; ++n) _Pragma("unroll") for (int k = 0; k < 2; ++k) dst[n][k] = *(const PG8_LAS bf16x8*)(lds + PG8_SB(b, h) + boff + n * 2048 + k * 1024); } while (0)
; #define PG8_MMA(ai, bj, At, Bt) do { __builtin_amdgcn_s_setprio(1); _Pragma("unroll") for (int m = 0; m < 4; ++m) _Pragma("unroll") for (int n = 0; n < 2; ++n) _Pragma("unroll") for (int k = 0; k < 2; ++k) \
;         acc[ai][bj][m][n] = __builtin_amdgcn_mfma_f32_16x16x32_bf16(Bt[n][k], At[m][k], acc[ai][bj][m][n], 0, 0, 0); __builtin_amdgcn_s_setprio(0); } while (0)
; #define PG8_WAIT_V(n) asm volatile("s_waitcnt vmcnt(" #n ")" ::: "memory")
; #define PG8_WAIT_L(n) asm volatile("s_waitcnt lgkmcnt(" #n ")" ::: "memory")
; #define PG8_BAR __builtin_amdgcn_s_barrier()
; #define PG8_SCHED __builtin_amdgcn_sched_barrier(0)
; template <class Epi>
; DI void gemm_phase(PG8_LAS unsigned char* lds, const Gemm g, const StaticOrder& S, const Epi& E) {
;     ...
;             PG8_WAIT_V(8); PG8_WAIT_L(0); PG8_BAR; PG8_MMA(1, 0, At, B0); PG8_MMA(1, 1, At, B1); PG8_BAR; PG8_SCHED;
;             PG8_LDB(B0, 1, 0); PG8_LDB(B1, 1, 1); PG8_SCHED; PG8_LDA(At, 1, 0); PG8_STAGE(PG8_SA(0, 1), a2 + hstepA, voffA);
;             PG8_WAIT_V(8); PG8_WAIT_L(0); PG8_BAR; PG8_MMA(0, 0, At, B0); PG8_MMA(0, 1, At, B1); PG8_BAR; PG8_SCHED;
	s_setprio 1
	s_waitcnt lgkmcnt(0)
	v_mfma_f32_16x16x32_bf16 v[60:63], v[144:147], v[182:185], v[60:63]
	v_mfma_f32_16x16x32_bf16 v[56:59], v[158:161], v[182:185], v[56:59]
	v_mfma_f32_16x16x32_bf16 v[44:47], v[144:147], v[190:193], v[44:47]
	v_mfma_f32_16x16x32_bf16 v[40:43], v[158:161], v[190:193], v[40:43]
	v_mfma_f32_16x16x32_bf16 v[28:31], v[144:147], v[198:201], v[28:31]
	v_mfma_f32_16x16x32_bf16 v[24:27], v[158:161], v[198:201], v[24:27]
	v_mfma_f32_16x16x32_bf16 v[12:15], v[144:147], v[206:209], v[12:15]
	v_mfma_f32_16x16x32_bf16 v[8:11], v[158:161], v[206:209], v[8:11]
	v_mfma_f32_16x16x32_bf16 v[60:63], v[148:151], v[186:189], v[60:63]
	v_mfma_f32_16x16x32_bf16 v[56:59], v[162:165], v[186:189], v[56:59]
	v_mfma_f32_16x16x32_bf16 v[44:47], v[148:151], v[194:197], v[44:47]
	v_mfma_f32_16x16x32_bf16 v[40:43], v[162:165], v[194:197], v[40:43]
	v_mfma_f32_16x16x32_bf16 v[28:31], v[148:151], v[202:205], v[28:31]
	v_mfma_f32_16x16x32_bf16 v[24:27], v[162:165], v[202:205], v[24:27]
	v_mfma_f32_16x16x32_bf16 v[12:15], v[148:151], v[210:213], v[12:15]
	v_mfma_f32_16x16x32_bf16 v[8:11], v[162:165], v[210:213], v[8:11]
	s_setprio 0
	s_setprio 1
	v_mfma_f32_16x16x32_bf16 v[52:55], v[166:169], v[182:185], v[52:55]
	v_mfma_f32_16x16x32_bf16 v[48:51], v[174:177], v[182:185], v[48:51]
	v_mfma_f32_16x16x32_bf16 v[36:39], v[166:169], v[190:193], v[36:39]
	v_mfma_f32_16x16x32_bf16 v[32:35], v[174:177], v[190:193], v[32:35]
	v_mfma_f32_16x16x32_bf16 v[20:23], v[166:169], v[198:201], v[20:23]
	v_mfma_f32_16x16x32_bf16 v[16:19], v[174:177], v[198:201], v[16:19]
	v_mfma_f32_16x16x32_bf16 v[4:7], v[166:169], v[206:209], v[4:7]
	v_mfma_f32_16x16x32_bf16 v[0:3], v[174:177], v[206:209], v[0:3]
	v_mfma_f32_16x16x32_bf16 v[52:55], v[170:173], v[186:189], v[52:55]
	v_mfma_f32_16x16x32_bf16 v[48:51], v[178:181], v[186:189], v[48:51]
	v_mfma_f32_16x16x32_bf16 v[36:39], v[170:173], v[194:197], v[36:39]
	v_mfma_f32_16x16x32_bf16 v[32:35], v[178:181], v[194:197], v[32:35]
	v_mfma_f32_16x16x32_bf16 v[20:23], v[170:173], v[202:205], v[20:23]
	v_mfma_f32_16x16x32_bf16 v[16:19], v[178:181], v[202:205], v[16:19]
	v_mfma_f32_16x16x32_bf16 v[4:7], v[170:173], v[210:213], v[4:7]
	v_mfma_f32_16x16x32_bf16 v[0:3], v[178:181], v[210:213], v[0:3]
	s_setprio 0
	s_barrier
	s_add_i32 s88, 16, 0x18000
	s_add_i32 s89, 16, 0x1c000
	v_add_u32_e32 v162, s88, v154
	v_add_u32_e32 v178, s89, v154
	ds_read_b128 v[144:147], v162
	ds_read_b128 v[148:151], v162 offset:1024
	ds_read_b128 v[158:161], v162 offset:2048
	ds_read_b128 v[162:165], v162 offset:3072
	ds_read_b128 v[166:169], v178
	ds_read_b128 v[170:173], v178 offset:1024
	ds_read_b128 v[174:177], v178 offset:2048
	ds_read_b128 v[178:181], v178 offset:3072
	s_add_u32 s34, s34, 0x40000
	s_addc_u32 s35, s35, 0
	s_mov_b32 m0, s40
	v_lshl_add_u64 v[222:223], s[34:35], 0, v[128:129]
	ds_read_b128 v[182:185], v157 offset:32768
	ds_read_b128 v[186:189], v157 offset:33792
	ds_read_b128 v[190:193], v157 offset:34816
	ds_read_b128 v[194:197], v157 offset:35840
	ds_read_b128 v[198:201], v157 offset:36864
	ds_read_b128 v[202:205], v157 offset:37888
	ds_read_b128 v[206:209], v157 offset:38912
	ds_read_b128 v[210:213], v157 offset:39936
	global_load_lds_dwordx4 v[222:223], off
	v_lshl_add_u64 v[222:223], s[34:35], 0, v[132:133]
	s_mov_b32 m0, s41
	s_nop 0
	global_load_lds_dwordx4 v[222:223], off
	s_waitcnt vmcnt(8)
	s_waitcnt lgkmcnt(0)
	s_barrier
	s_setprio 1
	s_waitcnt lgkmcnt(0)
	v_mfma_f32_16x16x32_bf16 v[124:127], v[144:147], v[182:185], v[124:127]
	v_mfma_f32_16x16x32_bf16 v[120:123], v[158:161], v[182:185], v[120:123]
	v_mfma_f32_16x16x32_bf16 v[108:111], v[144:147], v[190:193], v[108:111]
	v_mfma_f32_16x16x32_bf16 v[104:107], v[158:161], v[190:193], v[104:107]
	v_mfma_f32_16x16x32_bf16 v[92:95], v[144:147], v[198:201], v[92:95]
	v_mfma_f32_16x16x32_bf16 v[88:91], v[158:161], v[198:201], v[88:91]
	v_mfma_f32_16x16x32_bf16 v[76:79], v[144:147], v[206:209], v[76:79]
	v_mfma_f32_16x16x32_bf16 v[72:75], v[158:161], v[206:209], v[72:75]
	v_mfma_f32_16x16x32_bf16 v[124:127], v[148:151], v[186:189], v[124:127]
	v_mfma_f32_16x16x32_bf16 v[120:123], v[162:165], v[186:189], v[120:123]
	v_mfma_f32_16x16x32_bf16 v[108:111], v[148:151], v[194:197], v[108:111]
	v_mfma_f32_16x16x32_bf16 v[104:107], v[162:165], v[194:197], v[104:107]
	v_mfma_f32_16x16x32_bf16 v[92:95], v[148:151], v[202:205], v[92:95]
	v_mfma_f32_16x16x32_bf16 v[88:91], v[162:165], v[202:205], v[88:91]
	v_mfma_f32_16x16x32_bf16 v[76:79], v[148:151], v[210:213], v[76:79]
	v_mfma_f32_16x16x32_bf16 v[72:75], v[162:165], v[210:213], v[72:75]
	s_setprio 0
	s_setprio 1
	v_mfma_f32_16x16x32_bf16 v[116:119], v[166:169], v[182:185], v[116:119]
	v_mfma_f32_16x16x32_bf16 v[112:115], v[174:177], v[182:185], v[112:115]
	v_mfma_f32_16x16x32_bf16 v[100:103], v[166:169], v[190:193], v[100:103]
	v_mfma_f32_16x16x32_bf16 v[96:99], v[174:177], v[190:193], v[96:99]
	v_mfma_f32_16x16x32_bf16 v[84:87], v[166:169], v[198:201], v[84:87]
	v_mfma_f32_16x16x32_bf16 v[80:83], v[174:177], v[198:201], v[80:83]
	v_mfma_f32_16x16x32_bf16 v[68:71], v[166:169], v[206:209], v[68:71]
	v_mfma_f32_16x16x32_bf16 v[64:67], v[174:177], v[206:209], v[64:67]
	v_mfma_f32_16x16x32_bf16 v[116:119], v[170:173], v[186:189], v[116:119]
	v_mfma_f32_16x16x32_bf16 v[112:115], v[178:181], v[186:189], v[112:115]
	v_mfma_f32_16x16x32_bf16 v[100:103], v[170:173], v[194:197], v[100:103]
	v_mfma_f32_16x16x32_bf16 v[96:99], v[178:181], v[194:197], v[96:99]
	v_mfma_f32_16x16x32_bf16 v[84:87], v[170:173], v[202:205], v[84:87]
	v_mfma_f32_16x16x32_bf16 v[80:83], v[178:181], v[202:205], v[80:83]
	v_mfma_f32_16x16x32_bf16 v[68:71], v[170:173], v[210:213], v[68:71]
	v_mfma_f32_16x16x32_bf16 v[64:67], v[178:181], v[210:213], v[64:67]
	s_setprio 0
	s_barrier
; #define PG8_STAGE(bufoff, gbase, voff) do { _Pragma("unroll") for (int _i = 0; _i < 2; ++_i) \
;         __builtin_amdgcn_global_load_lds((const unsigned*)((const char*)(gbase) + (voff)[_i]), (PG8_LAS unsigned*)(lds + (bufoff) + ldsw + _i * 8192), 16, 0, 0); } while (0)
; #define PG8_LDA(dst, b, h) do { _Pragma("unroll") for (int m = 0; m < 4; ++m) _Pragma("unroll") for (int k = 0; k < 2; ++k) dst[m][k] = *(const PG8_LAS bf16x8*)(lds + PG8_SA(b, h) + aoff + m * 2048 + k * 1024); } while (0)
; #define PG8_MMA(ai, bj, At, Bt) do { __builtin_amdgcn_s_setprio(1); _Pragma("unroll") for (int m = 0; m < 4; ++m) _Pragma("unroll") for (int n = 0; n < 2; ++n) _Pragma("unroll") for (int k = 0; k < 2; ++k) \
;         acc[ai][bj][m][n] = __builtin_amdgcn_mfma_f32_16x16x32_bf16(Bt[n][k], At[m][k], acc[ai][bj][m][n], 0, 0, 0); __builtin_amdgcn_s_setprio(0); } while (0)
; #define PG8_WAIT_V(n) asm volatile("s_waitcnt vmcnt(" #n ")" ::: "memory")
; #define PG8_WAIT_L(n) asm volatile("s_waitcnt lgkmcnt(" #n ")" ::: "memory")
; #define PG8_BAR __builtin_amdgcn_s_barrier()
; #define PG8_SCHED __builtin_amdgcn_sched_barrier(0)
; template <class Epi>
; DI void gemm_phase(PG8_LAS unsigned char* lds, const Gemm g, const StaticOrder& S, const Epi& E) {
;     ...
;             PG8_LDA(At, 1, 1); PG8_STAGE(PG8_SB(1, 0), b3, voffB); PG8_STAGE(PG8_SB(1, 1), b3 + hstepB, voffB); PG8_STAGE(PG8_SA(1, 0), a3, voffA);
;             PG8_WAIT_V(8); PG8_WAIT_L(0); PG8_BAR; PG8_MMA(1, 0, At, B0); PG8_MMA(1, 1, At, B1); PG8_BAR; PG8_SCHED;
;         }
;         if (wr == 0) PG8_BAR;
	s_add_i32 s34, s88, s38
	v_lshl_add_u64 v[214:215], v[214:215], 0, s[14:15]
	s_mov_b32 m0, s34
	ds_read_b128 v[182:185], v157 offset:49152
	ds_read_b128 v[186:189], v157 offset:50176
	ds_read_b128 v[190:193], v157 offset:51200
	ds_read_b128 v[194:197], v157 offset:52224
	ds_read_b128 v[198:201], v157 offset:53248
	ds_read_b128 v[202:205], v157 offset:54272
	ds_read_b128 v[206:209], v157 offset:55296
	ds_read_b128 v[210:213], v157 offset:56320
	global_load_lds_dwordx4 v[214:215], off
	s_add_i32 m0, s34, 0x2000
	s_add_u32 s30, s30, 0x40080
	v_lshl_add_u64 v[214:215], v[216:217], 0, s[14:15]
	s_addc_u32 s31, s31, 0
	s_add_i32 s34, s89, s38
	global_load_lds_dwordx4 v[214:215], off
	v_lshl_add_u64 v[214:215], s[30:31], 0, v[130:131]
	s_mov_b32 m0, s34
	s_nop 0
	global_load_lds_dwordx4 v[214:215], off
	v_lshl_add_u64 v[214:215], s[30:31], 0, v[134:135]
	s_add_i32 m0, s34, 0x2000
	s_nop 0
	global_load_lds_dwordx4 v[214:215], off
	v_lshl_add_u64 v[214:215], v[218:219], 0, s[14:15]
	s_mov_b32 m0, s45
	s_nop 0
	global_load_lds_dwordx4 v[214:215], off
	v_lshl_add_u64 v[214:215], v[220:221], 0, s[14:15]
	s_mov_b32 m0, s46
	s_nop 0
	global_load_lds_dwordx4 v[214:215], off
	s_waitcnt vmcnt(8)
	s_waitcnt lgkmcnt(0)
	s_barrier
	s_setprio 1
	s_waitcnt lgkmcnt(0)
	v_mfma_f32_16x16x32_bf16 v[60:63], v[144:147], v[182:185], v[60:63]
	v_mfma_f32_16x16x32_bf16 v[56:59], v[158:161], v[182:185], v[56:59]
	v_mfma_f32_16x16x32_bf16 v[44:47], v[144:147], v[190:193], v[44:47]
	v_mfma_f32_16x16x32_bf16 v[40:43], v[158:161], v[190:193], v[40:43]
	v_mfma_f32_16x16x32_bf16 v[28:31], v[144:147], v[198:201], v[28:31]
	v_mfma_f32_16x16x32_bf16 v[24:27], v[158:161], v[198:201], v[24:27]
	v_mfma_f32_16x16x32_bf16 v[12:15], v[144:147], v[206:209], v[12:15]
	v_mfma_f32_16x16x32_bf16 v[8:11], v[158:161], v[206:209], v[8:11]
	v_mfma_f32_16x16x32_bf16 v[60:63], v[148:151], v[186:189], v[60:63]
	v_mfma_f32_16x16x32_bf16 v[56:59], v[162:165], v[186:189], v[56:59]
	v_mfma_f32_16x16x32_bf16 v[44:47], v[148:151], v[194:197], v[44:47]
	v_mfma_f32_16x16x32_bf16 v[40:43], v[162:165], v[194:197], v[40:43]
	v_mfma_f32_16x16x32_bf16 v[28:31], v[148:151], v[202:205], v[28:31]
	v_mfma_f32_16x16x32_bf16 v[24:27], v[162:165], v[202:205], v[24:27]
	v_mfma_f32_16x16x32_bf16 v[12:15], v[148:151], v[210:213], v[12:15]
	v_mfma_f32_16x16x32_bf16 v[8:11], v[162:165], v[210:213], v[8:11]
	s_setprio 0
	s_setprio 1
	v_mfma_f32_16x16x32_bf16 v[52:55], v[166:169], v[182:185], v[52:55]
	v_mfma_f32_16x16x32_bf16 v[48:51], v[174:177], v[182:185], v[48:51]
	v_mfma_f32_16x16x32_bf16 v[36:39], v[166:169], v[190:193], v[36:39]
	v_mfma_f32_16x16x32_bf16 v[32:35], v[174:177], v[190:193], v[32:35]
	v_mfma_f32_16x16x32_bf16 v[20:23], v[166:169], v[198:201], v[20:23]
	v_mfma_f32_16x16x32_bf16 v[16:19], v[174:177], v[198:201], v[16:19]
	v_mfma_f32_16x16x32_bf16 v[4:7], v[166:169], v[206:209], v[4:7]
	v_mfma_f32_16x16x32_bf16 v[0:3], v[174:177], v[206:209], v[0:3]
	v_mfma_f32_16x16x32_bf16 v[52:55], v[170:173], v[186:189], v[52:55]
	v_mfma_f32_16x16x32_bf16 v[48:51], v[178:181], v[186:189], v[48:51]
	v_mfma_f32_16x16x32_bf16 v[36:39], v[170:173], v[194:197], v[36:39]
	v_mfma_f32_16x16x32_bf16 v[32:35], v[178:181], v[194:197], v[32:35]
	v_mfma_f32_16x16x32_bf16 v[20:23], v[170:173], v[202:205], v[20:23]
	v_mfma_f32_16x16x32_bf16 v[16:19], v[178:181], v[202:205], v[16:19]
	v_mfma_f32_16x16x32_bf16 v[4:7], v[170:173], v[210:213], v[4:7]
	v_mfma_f32_16x16x32_bf16 v[0:3], v[178:181], v[210:213], v[0:3]
	s_setprio 0
	s_add_i32 s91, s91, 2
	s_add_u32 s28, s28, 0x100
	s_addc_u32 s29, s29, 0
	s_add_u32 s87, s87, 0x100
	s_addc_u32 s90, s90, 0
	s_cmp_gt_u32 s91, 13
	s_barrier
	s_cbranch_scc0 .LBB0_852
	s_and_b64 vcc, exec, s[16:17]
	s_cbranch_vccz .LBB0_855
	s_barrier

; #define PG8_STAGE(bufoff, gbase, voff) do { _Pragma("unroll") for (int _i = 0; _i < 2; ++_i) \
;         __builtin_amdgcn_global_load_lds((const unsigned*)((const char*)(gbase) + (voff)[_i]), (PG8_LAS unsigned*)(lds + (bufoff) + ldsw + _i * 8192), 16, 0, 0); } while (0)
; #define PG8_LDA(dst, b, h) do { _Pragma("unroll") for (int m = 0; m < 4; ++m) _Pragma("unroll") for (int k = 0; k < 2; ++k) dst[m][k] = *(const PG8_LAS bf16x8*)(lds + PG8_SA(b, h) + aoff + m * 2048 + k * 1024); } while (0)
; #define PG8_LDB(dst, b, h) do { _Pragma("unroll") for (int n = 0; n < 2; ++n) _Pragma("unroll") for (int k = 0; k < 2; ++k) dst[n][k] = *(const PG8_LAS bf16x8*)(lds + PG8_SB(b, h) + boff + n * 2048 + k * 1024); } while (0)
; #define PG8_MMA(ai, bj, At, Bt) do { __builtin_amdgcn_s_setprio(1); _Pragma("unroll") for (int m = 0; m < 4; ++m) _Pragma("unroll") for (int n = 0; n < 2; ++n) _Pragma("unroll") for (int k = 0; k < 2; ++k) \
;         acc[ai][bj][m][n] = __builtin_amdgcn_mfma_f32_16x16x32_bf16(Bt[n][k], At[m][k], acc[ai][bj][m][n], 0, 0, 0); __builtin_amdgcn_s_setprio(0); } while (0)
; #define PG8_WAIT_V(n) asm volatile("s_waitcnt vmcnt(" #n ")" ::: "memory")
; #define PG8_WAIT_L(n) asm volatile("s_waitcnt lgkmcnt(" #n ")" ::: "memory")
; #define PG8_BAR __builtin_amdgcn_s_barrier()
; #define PG8_SCHED __builtin_amdgcn_sched_barrier(0)
; template <class Epi>
; DI void gemm_phase(PG8_LAS unsigned char* lds, const Gemm g, const StaticOrder& S, const Epi& E) {
;     ...
;         for (int t = 0; t < nt; t += 2) {
;             const bool last = (t == nt - 2);
;             const char* a1 = cA + (size_t)(t + 1) * kstep;
;             const char* a2 = last ? nA : cA + (size_t)(t + 2) * kstep; const char* b2 = last ? nB : cB + (size_t)(t + 2) * kstep;
;             const char* a3 = a2 + kstep; const char* b3 = b2 + kstep;
;             PG8_LDB(B0, 0, 0); PG8_LDB(B1, 0, 1); PG8_SCHED; PG8_LDA(At, 0, 0); PG8_STAGE(PG8_SA(1, 1), a1 + hstepA, voffA);
;             PG8_WAIT_V(8); PG8_WAIT_L(0); PG8_BAR; PG8_MMA(0, 0, At, B0); PG8_MMA(0, 1, At, B1); PG8_BAR; PG8_SCHED;
;             PG8_LDA(At, 0, 1); PG8_STAGE(PG8_SB(0, 0), b2, voffB); PG8_STAGE(PG8_SB(0, 1), b2 + hstepB, voffB); PG8_STAGE(PG8_SA(0, 0), a2, voffA);
;             PG8_WAIT_V(8); PG8_WAIT_L(0); PG8_BAR; PG8_MMA(1, 0, At, B0); PG8_MMA(1, 1, At, B1); PG8_BAR; PG8_SCHED;
.LBB0_928:
	ds_read_b128 v[144:147], v167
	ds_read_b128 v[148:151], v167 offset:1024
	ds_read_b128 v[152:155], v167 offset:2048
	ds_read_b128 v[156:159], v167 offset:3072
	ds_read_b128 v[160:163], v168
	ds_read_b128 v[170:173], v168 offset:1024
	ds_read_b128 v[174:177], v168 offset:2048
	ds_read_b128 v[178:181], v168 offset:3072
	s_add_u32 s40, s38, 0xfffc0080
	s_addc_u32 s41, s39, -1
	s_cmp_eq_u32 s91, 12
	s_cselect_b32 s43, s29, s41
	s_cselect_b32 s42, s85, s40
	s_cselect_b32 s41, s27, s90
	s_cselect_b32 s40, s86, s87
	v_lshl_add_u64 v[214:215], s[38:39], 0, v[136:137]
	s_add_i32 m0, s46, 0xc000
	ds_read_b128 v[182:185], v169
	ds_read_b128 v[186:189], v169 offset:1024
	ds_read_b128 v[190:193], v169 offset:2048
	ds_read_b128 v[194:197], v169 offset:3072
	ds_read_b128 v[198:201], v169 offset:4096
	ds_read_b128 v[202:205], v169 offset:5120
	ds_read_b128 v[206:209], v169 offset:6144
	ds_read_b128 v[210:213], v169 offset:7168
	global_load_lds_dwordx4 v[214:215], off
	v_lshl_add_u64 v[214:215], s[38:39], 0, v[138:139]
	s_add_i32 m0, s46, 0xe000
	s_nop 0
	global_load_lds_dwordx4 v[214:215], off
	s_waitcnt vmcnt(8)
	s_waitcnt lgkmcnt(0)
	s_barrier
	s_setprio 1
	s_waitcnt lgkmcnt(0)
	v_mfma_f32_16x16x32_bf16 v[124:127], v[144:147], v[182:185], v[124:127]
	v_mfma_f32_16x16x32_bf16 v[120:123], v[152:155], v[182:185], v[120:123]
	v_mfma_f32_16x16x32_bf16 v[108:111], v[144:147], v[190:193], v[108:111]
	v_mfma_f32_16x16x32_bf16 v[104:107], v[152:155], v[190:193], v[104:107]
	v_mfma_f32_16x16x32_bf16 v[92:95], v[144:147], v[198:201], v[92:95]
	v_mfma_f32_16x16x32_bf16 v[88:91], v[152:155], v[198:201], v[88:91]
	v_mfma_f32_16x16x32_bf16 v[76:79], v[144:147], v[206:209], v[76:79]
	v_mfma_f32_16x16x32_bf16 v[72:75], v[152:155], v[206:209], v[72:75]
	v_mfma_f32_16x16x32_bf16 v[124:127], v[148:151], v[186:189], v[124:127]
	v_mfma_f32_16x16x32_bf16 v[120:123], v[156:159], v[186:189], v[120:123]
	v_mfma_f32_16x16x32_bf16 v[108:111], v[148:151], v[194:197], v[108:111]
	v_mfma_f32_16x16x32_bf16 v[104:107], v[156:159], v[194:197], v[104:107]
	v_mfma_f32_16x16x32_bf16 v[92:95], v[148:151], v[202:205], v[92:95]
	v_mfma_f32_16x16x32_bf16 v[88:91], v[156:159], v[202:205], v[88:91]
	v_mfma_f32_16x16x32_bf16 v[76:79], v[148:151], v[210:213], v[76:79]
	v_mfma_f32_16x16x32_bf16 v[72:75], v[156:159], v[210:213], v[72:75]
	s_setprio 0
	s_setprio 1
	v_mfma_f32_16x16x32_bf16 v[116:119], v[160:163], v[182:185], v[116:119]
	v_mfma_f32_16x16x32_bf16 v[112:115], v[174:177], v[182:185], v[112:115]
	v_mfma_f32_16x16x32_bf16 v[100:103], v[160:163], v[190:193], v[100:103]
	v_mfma_f32_16x16x32_bf16 v[96:99], v[174:177], v[190:193], v[96:99]
	v_mfma_f32_16x16x32_bf16 v[84:87], v[160:163], v[198:201], v[84:87]
	v_mfma_f32_16x16x32_bf16 v[80:83], v[174:177], v[198:201], v[80:83]
	v_mfma_f32_16x16x32_bf16 v[68:71], v[160:163], v[206:209], v[68:71]
	v_mfma_f32_16x16x32_bf16 v[64:67], v[174:177], v[206:209], v[64:67]
	v_mfma_f32_16x16x32_bf16 v[116:119], v[170:173], v[186:189], v[116:119]
	v_mfma_f32_16x16x32_bf16 v[112:115], v[178:181], v[186:189], v[112:115]
	v_mfma_f32_16x16x32_bf16 v[100:103], v[170:173], v[194:197], v[100:103]
	v_mfma_f32_16x16x32_bf16 v[96:99], v[178:181], v[194:197], v[96:99]
	v_mfma_f32_16x16x32_bf16 v[84:87], v[170:173], v[202:205], v[84:87]
	v_mfma_f32_16x16x32_bf16 v[80:83], v[178:181], v[202:205], v[80:83]
	v_mfma_f32_16x16x32_bf16 v[68:71], v[170:173], v[210:213], v[68:71]
	v_mfma_f32_16x16x32_bf16 v[64:67], v[178:181], v[210:213], v[64:67]
	s_setprio 0
	s_barrier
	s_add_i32 s88, s57, s45
	v_lshl_add_u64 v[214:215], s[40:41], 0, v[130:131]
	s_mov_b32 m0, s88
	ds_read_b128 v[182:185], v169 offset:16384
	ds_read_b128 v[186:189], v169 offset:17408
	ds_read_b128 v[190:193], v169 offset:18432
	ds_read_b128 v[194:197], v169 offset:19456
	ds_read_b128 v[198:201], v169 offset:20480
	ds_read_b128 v[202:205], v169 offset:21504
	ds_read_b128 v[206:209], v169 offset:22528
	ds_read_b128 v[210:213], v169 offset:23552
	global_load_lds_dwordx4 v[214:215], off
	s_add_i32 m0, s88, 0x2000
	s_add_u32 s92, s40, 0x40000
	v_lshl_add_u64 v[216:217], s[40:41], 0, v[134:135]
	s_addc_u32 s93, s41, 0
	s_add_i32 s88, s76, s45
	global_load_lds_dwordx4 v[216:217], off
	v_lshl_add_u64 v[218:219], s[92:93], 0, v[130:131]
	s_mov_b32 m0, s88
	v_lshl_add_u64 v[220:221], s[42:43], 0, v[132:133]
	global_load_lds_dwordx4 v[218:219], off
	v_lshl_add_u64 v[218:219], s[92:93], 0, v[134:135]
	s_add_i32 m0, s88, 0x2000
	s_nop 0
	global_load_lds_dwordx4 v[218:219], off
	v_lshl_add_u64 v[218:219], s[42:43], 0, v[128:129]
	s_mov_b32 m0, s46
	s_nop 0
	global_load_lds_dwordx4 v[218:219], off
	s_mov_b32 m0, s47
	s_nop 0
	global_load_lds_dwordx4 v[220:221], off
	s_waitcnt vmcnt(8)
	s_waitcnt lgkmcnt(0)
	s_barrier
; #define PG8_STAGE(bufoff, gbase, voff) do { _Pragma("unroll") for (int _i = 0; _i < 2; ++_i) \
;         __builtin_amdgcn_global_load_lds((const unsigned*)((const char*)(gbase) + (voff)[_i]), (PG8_LAS unsigned*)(lds + (bufoff) + ldsw + _i * 8192), 16, 0, 0); } while (0)
; #define PG8_LDA(dst, b, h) do { _Pragma("unroll") for (int m = 0; m < 4; ++m) _Pragma("unroll") for (int k = 0; k < 2; ++k) dst[m][k] = *(const PG8_LAS bf16x8*)(lds + PG8_SA(b, h) + aoff + m * 2048 + k * 1024); } while (0)
; #define PG8_LDB(dst, b, h) do { _Pragma("unroll") for (int n = 0; n < 2; ++n) _Pragma("unroll") for (int k = 0; k < 2; ++k) dst[n][k] = *(const PG8_LAS bf16x8*)(lds + PG8_SB(b, h) + boff + n * 2048 + k * 1024); } while (0)
; #define PG8_MMA(ai, bj, At, Bt) do { __builtin_amdgcn_s_setprio(1); _Pragma("unroll") for (int m = 0; m < 4; ++m) _Pragma("unroll") for (int n = 0; n < 2; ++n) _Pragma("unroll") for (int k = 0; k < 2; ++k) \
;         acc[ai][bj][m][n] = __builtin_amdgcn_mfma_f32_16x16x32_bf16(Bt[n][k], At[m][k], acc[ai][bj][m][n], 0, 0, 0); __builtin_amdgcn_s_setprio(0); } while (0)
; #define PG8_WAIT_V(n) asm volatile("s_waitcnt vmcnt(" #n ")" ::: "memory")
; #define PG8_WAIT_L(n) asm volatile("s_waitcnt lgkmcnt(" #n ")" ::: "memory")
; #define PG8_BAR __builtin_amdgcn_s_barrier()
; #define PG8_SCHED __builtin_amdgcn_sched_barrier(0)
; template <class Epi>
; DI void gemm_phase(PG8_LAS unsigned char* lds, const Gemm g, const StaticOrder& S, const Epi& E) {
;     ...
;             PG8_WAIT_V(8); PG8_WAIT_L(0); PG8_BAR; PG8_MMA(1, 0, At, B0); PG8_MMA(1, 1, At, B1); PG8_BAR; PG8_SCHED;
;             PG8_LDB(B0, 1, 0); PG8_LDB(B1, 1, 1); PG8_SCHED; PG8_LDA(At, 1, 0); PG8_STAGE(PG8_SA(0, 1), a2 + hstepA, voffA);
;             PG8_WAIT_V(8); PG8_WAIT_L(0); PG8_BAR; PG8_MMA(0, 0, At, B0); PG8_MMA(0, 1, At, B1); PG8_BAR; PG8_SCHED;
	s_setprio 1
	s_waitcnt lgkmcnt(0)
	v_mfma_f32_16x16x32_bf16 v[60:63], v[144:147], v[182:185], v[60:63]
	v_mfma_f32_16x16x32_bf16 v[56:59], v[152:155], v[182:185], v[56:59]
	v_mfma_f32_16x16x32_bf16 v[44:47], v[144:147], v[190:193], v[44:47]
	v_mfma_f32_16x16x32_bf16 v[40:43], v[152:155], v[190:193], v[40:43]
	v_mfma_f32_16x16x32_bf16 v[28:31], v[144:147], v[198:201], v[28:31]
	v_mfma_f32_16x16x32_bf16 v[24:27], v[152:155], v[198:201], v[24:27]
	v_mfma_f32_16x16x32_bf16 v[12:15], v[144:147], v[206:209], v[12:15]
	v_mfma_f32_16x16x32_bf16 v[8:11], v[152:155], v[206:209], v[8:11]
	v_mfma_f32_16x16x32_bf16 v[60:63], v[148:151], v[186:189], v[60:63]
	v_mfma_f32_16x16x32_bf16 v[56:59], v[156:159], v[186:189], v[56:59]
	v_mfma_f32_16x16x32_bf16 v[44:47], v[148:151], v[194:197], v[44:47]
	v_mfma_f32_16x16x32_bf16 v[40:43], v[156:159], v[194:197], v[40:43]
	v_mfma_f32_16x16x32_bf16 v[28:31], v[148:151], v[202:205], v[28:31]
	v_mfma_f32_16x16x32_bf16 v[24:27], v[156:159], v[202:205], v[24:27]
	v_mfma_f32_16x16x32_bf16 v[12:15], v[148:151], v[210:213], v[12:15]
	v_mfma_f32_16x16x32_bf16 v[8:11], v[156:159], v[210:213], v[8:11]
	s_setprio 0
	s_setprio 1
	v_mfma_f32_16x16x32_bf16 v[52:55], v[160:163], v[182:185], v[52:55]
	v_mfma_f32_16x16x32_bf16 v[48:51], v[174:177], v[182:185], v[48:51]
	v_mfma_f32_16x16x32_bf16 v[36:39], v[160:163], v[190:193], v[36:39]
	v_mfma_f32_16x16x32_bf16 v[32:35], v[174:177], v[190:193], v[32:35]
	v_mfma_f32_16x16x32_bf16 v[20:23], v[160:163], v[198:201], v[20:23]
	v_mfma_f32_16x16x32_bf16 v[16:19], v[174:177], v[198:201], v[16:19]
	v_mfma_f32_16x16x32_bf16 v[4:7], v[160:163], v[206:209], v[4:7]
	v_mfma_f32_16x16x32_bf16 v[0:3], v[174:177], v[206:209], v[0:3]
	v_mfma_f32_16x16x32_bf16 v[52:55], v[170:173], v[186:189], v[52:55]
	v_mfma_f32_16x16x32_bf16 v[48:51], v[178:181], v[186:189], v[48:51]
	v_mfma_f32_16x16x32_bf16 v[36:39], v[170:173], v[194:197], v[36:39]
	v_mfma_f32_16x16x32_bf16 v[32:35], v[178:181], v[194:197], v[32:35]
	v_mfma_f32_16x16x32_bf16 v[20:23], v[170:173], v[202:205], v[20:23]
	v_mfma_f32_16x16x32_bf16 v[16:19], v[178:181], v[202:205], v[16:19]
	v_mfma_f32_16x16x32_bf16 v[4:7], v[170:173], v[210:213], v[4:7]
	v_mfma_f32_16x16x32_bf16 v[0:3], v[178:181], v[210:213], v[0:3]
	s_setprio 0
	s_barrier
	s_add_i32 s88, 16, 0x18000
	s_add_i32 s89, 16, 0x1c000
	v_add_u32_e32 v156, s88, v166
	v_add_u32_e32 v178, s89, v166
	ds_read_b128 v[144:147], v156
	ds_read_b128 v[148:151], v156 offset:1024
	ds_read_b128 v[152:155], v156 offset:2048
	ds_read_b128 v[156:159], v156 offset:3072
	ds_read_b128 v[160:163], v178
	ds_read_b128 v[170:173], v178 offset:1024
	ds_read_b128 v[174:177], v178 offset:2048
	ds_read_b128 v[178:181], v178 offset:3072
	s_add_u32 s42, s42, 0x40000
	s_addc_u32 s43, s43, 0
	s_mov_b32 m0, s48
	v_lshl_add_u64 v[222:223], s[42:43], 0, v[128:129]
	ds_read_b128 v[182:185], v169 offset:32768
	ds_read_b128 v[186:189], v169 offset:33792
	ds_read_b128 v[190:193], v169 offset:34816
	ds_read_b128 v[194:197], v169 offset:35840
	ds_read_b128 v[198:201], v169 offset:36864
	ds_read_b128 v[202:205], v169 offset:37888
	ds_read_b128 v[206:209], v169 offset:38912
	ds_read_b128 v[210:213], v169 offset:39936
	global_load_lds_dwordx4 v[222:223], off
	v_lshl_add_u64 v[222:223], s[42:43], 0, v[132:133]
	s_mov_b32 m0, s49
	s_nop 0
	global_load_lds_dwordx4 v[222:223], off
	s_waitcnt vmcnt(8)
	s_waitcnt lgkmcnt(0)
	s_barrier
	s_setprio 1
	s_waitcnt lgkmcnt(0)
	v_mfma_f32_16x16x32_bf16 v[124:127], v[144:147], v[182:185], v[124:127]
	v_mfma_f32_16x16x32_bf16 v[120:123], v[152:155], v[182:185], v[120:123]
	v_mfma_f32_16x16x32_bf16 v[108:111], v[144:147], v[190:193], v[108:111]
	v_mfma_f32_16x16x32_bf16 v[104:107], v[152:155], v[190:193], v[104:107]
	v_mfma_f32_16x16x32_bf16 v[92:95], v[144:147], v[198:201], v[92:95]
	v_mfma_f32_16x16x32_bf16 v[88:91], v[152:155], v[198:201], v[88:91]
	v_mfma_f32_16x16x32_bf16 v[76:79], v[144:147], v[206:209], v[76:79]
	v_mfma_f32_16x16x32_bf16 v[72:75], v[152:155], v[206:209], v[72:75]
	v_mfma_f32_16x16x32_bf16 v[124:127], v[148:151], v[186:189], v[124:127]
	v_mfma_f32_16x16x32_bf16 v[120:123], v[156:159], v[186:189], v[120:123]
	v_mfma_f32_16x16x32_bf16 v[108:111], v[148:151], v[194:197], v[108:111]
	v_mfma_f32_16x16x32_bf16 v[104:107], v[156:159], v[194:197], v[104:107]
	v_mfma_f32_16x16x32_bf16 v[92:95], v[148:151], v[202:205], v[92:95]
	v_mfma_f32_16x16x32_bf16 v[88:91], v[156:159], v[202:205], v[88:91]
	v_mfma_f32_16x16x32_bf16 v[76:79], v[148:151], v[210:213], v[76:79]
	v_mfma_f32_16x16x32_bf16 v[72:75], v[156:159], v[210:213], v[72:75]
	s_setprio 0
	s_setprio 1
	v_mfma_f32_16x16x32_bf16 v[116:119], v[160:163], v[182:185], v[116:119]
	v_mfma_f32_16x16x32_bf16 v[112:115], v[174:177], v[182:185], v[112:115]
	v_mfma_f32_16x16x32_bf16 v[100:103], v[160:163], v[190:193], v[100:103]
	v_mfma_f32_16x16x32_bf16 v[96:99], v[174:177], v[190:193], v[96:99]
	v_mfma_f32_16x16x32_bf16 v[84:87], v[160:163], v[198:201], v[84:87]
	v_mfma_f32_16x16x32_bf16 v[80:83], v[174:177], v[198:201], v[80:83]
	v_mfma_f32_16x16x32_bf16 v[68:71], v[160:163], v[206:209], v[68:71]
	v_mfma_f32_16x16x32_bf16 v[64:67], v[174:177], v[206:209], v[64:67]
	v_mfma_f32_16x16x32_bf16 v[116:119], v[170:173], v[186:189], v[116:119]
	v_mfma_f32_16x16x32_bf16 v[112:115], v[178:181], v[186:189], v[112:115]
	v_mfma_f32_16x16x32_bf16 v[100:103], v[170:173], v[194:197], v[100:103]
	v_mfma_f32_16x16x32_bf16 v[96:99], v[178:181], v[194:197], v[96:99]
	v_mfma_f32_16x16x32_bf16 v[84:87], v[170:173], v[202:205], v[84:87]
	v_mfma_f32_16x16x32_bf16 v[80:83], v[178:181], v[202:205], v[80:83]
	v_mfma_f32_16x16x32_bf16 v[68:71], v[170:173], v[210:213], v[68:71]
	v_mfma_f32_16x16x32_bf16 v[64:67], v[178:181], v[210:213], v[64:67]
	s_setprio 0
	s_barrier
; #define PG8_STAGE(bufoff, gbase, voff) do { _Pragma("unroll") for (int _i = 0; _i < 2; ++_i) \
;         __builtin_amdgcn_global_load_lds((const unsigned*)((const char*)(gbase) + (voff)[_i]), (PG8_LAS unsigned*)(lds + (bufoff) + ldsw + _i * 8192), 16, 0, 0); } while (0)
; #define PG8_LDA(dst, b, h) do { _Pragma("unroll") for (int m = 0; m < 4; ++m) _Pragma("unroll") for (int k = 0; k < 2; ++k) dst[m][k] = *(const PG8_LAS bf16x8*)(lds + PG8_SA(b, h) + aoff + m * 2048 + k * 1024); } while (0)
; #define PG8_MMA(ai, bj, At, Bt) do { __builtin_amdgcn_s_setprio(1); _Pragma("unroll") for (int m = 0; m < 4; ++m) _Pragma("unroll") for (int n = 0; n < 2; ++n) _Pragma("unroll") for (int k = 0; k < 2; ++k) \
;         acc[ai][bj][m][n] = __builtin_amdgcn_mfma_f32_16x16x32_bf16(Bt[n][k], At[m][k], acc[ai][bj][m][n], 0, 0, 0); __builtin_amdgcn_s_setprio(0); } while (0)
; #define PG8_WAIT_V(n) asm volatile("s_waitcnt vmcnt(" #n ")" ::: "memory")
; #define PG8_WAIT_L(n) asm volatile("s_waitcnt lgkmcnt(" #n ")" ::: "memory")
; #define PG8_BAR __builtin_amdgcn_s_barrier()
; #define PG8_SCHED __builtin_amdgcn_sched_barrier(0)
; template <class Epi>
; DI void gemm_phase(PG8_LAS unsigned char* lds, const Gemm g, const StaticOrder& S, const Epi& E) {
;     ...
;             PG8_LDA(At, 1, 1); PG8_STAGE(PG8_SB(1, 0), b3, voffB); PG8_STAGE(PG8_SB(1, 1), b3 + hstepB, voffB); PG8_STAGE(PG8_SA(1, 0), a3, voffA);
;             PG8_WAIT_V(8); PG8_WAIT_L(0); PG8_BAR; PG8_MMA(1, 0, At, B0); PG8_MMA(1, 1, At, B1); PG8_BAR; PG8_SCHED;
;         }
;         if (wr == 0) PG8_BAR;
	s_add_i32 s42, s88, s45
	v_lshl_add_u64 v[214:215], v[214:215], 0, s[10:11]
	s_mov_b32 m0, s42
	ds_read_b128 v[182:185], v169 offset:49152
	ds_read_b128 v[186:189], v169 offset:50176
	ds_read_b128 v[190:193], v169 offset:51200
	ds_read_b128 v[194:197], v169 offset:52224
	ds_read_b128 v[198:201], v169 offset:53248
	ds_read_b128 v[202:205], v169 offset:54272
	ds_read_b128 v[206:209], v169 offset:55296
	ds_read_b128 v[210:213], v169 offset:56320
	global_load_lds_dwordx4 v[214:215], off
	s_add_i32 m0, s42, 0x2000
	s_add_u32 s40, s40, 0x40080
	v_lshl_add_u64 v[214:215], v[216:217], 0, s[10:11]
	s_addc_u32 s41, s41, 0
	s_add_i32 s42, s89, s45
	global_load_lds_dwordx4 v[214:215], off
	v_lshl_add_u64 v[214:215], s[40:41], 0, v[130:131]
	s_mov_b32 m0, s42
	s_nop 0
	global_load_lds_dwordx4 v[214:215], off
	v_lshl_add_u64 v[214:215], s[40:41], 0, v[134:135]
	s_add_i32 m0, s42, 0x2000
	s_nop 0
	global_load_lds_dwordx4 v[214:215], off
	v_lshl_add_u64 v[214:215], v[218:219], 0, s[10:11]
	s_mov_b32 m0, s53
	s_nop 0
	global_load_lds_dwordx4 v[214:215], off
	v_lshl_add_u64 v[214:215], v[220:221], 0, s[10:11]
	s_mov_b32 m0, s54
	s_nop 0
	global_load_lds_dwordx4 v[214:215], off
	s_waitcnt vmcnt(8)
	s_waitcnt lgkmcnt(0)
	s_barrier
	s_setprio 1
	s_waitcnt lgkmcnt(0)
	v_mfma_f32_16x16x32_bf16 v[60:63], v[144:147], v[182:185], v[60:63]
	v_mfma_f32_16x16x32_bf16 v[56:59], v[152:155], v[182:185], v[56:59]
	v_mfma_f32_16x16x32_bf16 v[44:47], v[144:147], v[190:193], v[44:47]
	v_mfma_f32_16x16x32_bf16 v[40:43], v[152:155], v[190:193], v[40:43]
	v_mfma_f32_16x16x32_bf16 v[28:31], v[144:147], v[198:201], v[28:31]
	v_mfma_f32_16x16x32_bf16 v[24:27], v[152:155], v[198:201], v[24:27]
	v_mfma_f32_16x16x32_bf16 v[12:15], v[144:147], v[206:209], v[12:15]
	v_mfma_f32_16x16x32_bf16 v[8:11], v[152:155], v[206:209], v[8:11]
	v_mfma_f32_16x16x32_bf16 v[60:63], v[148:151], v[186:189], v[60:63]
	v_mfma_f32_16x16x32_bf16 v[56:59], v[156:159], v[186:189], v[56:59]
	v_mfma_f32_16x16x32_bf16 v[44:47], v[148:151], v[194:197], v[44:47]
	v_mfma_f32_16x16x32_bf16 v[40:43], v[156:159], v[194:197], v[40:43]
	v_mfma_f32_16x16x32_bf16 v[28:31], v[148:151], v[202:205], v[28:31]
	v_mfma_f32_16x16x32_bf16 v[24:27], v[156:159], v[202:205], v[24:27]
	v_mfma_f32_16x16x32_bf16 v[12:15], v[148:151], v[210:213], v[12:15]
	v_mfma_f32_16x16x32_bf16 v[8:11], v[156:159], v[210:213], v[8:11]
	s_setprio 0
	s_setprio 1
	v_mfma_f32_16x16x32_bf16 v[52:55], v[160:163], v[182:185], v[52:55]
	v_mfma_f32_16x16x32_bf16 v[48:51], v[174:177], v[182:185], v[48:51]
	v_mfma_f32_16x16x32_bf16 v[36:39], v[160:163], v[190:193], v[36:39]
	v_mfma_f32_16x16x32_bf16 v[32:35], v[174:177], v[190:193], v[32:35]
	v_mfma_f32_16x16x32_bf16 v[20:23], v[160:163], v[198:201], v[20:23]
	v_mfma_f32_16x16x32_bf16 v[16:19], v[174:177], v[198:201], v[16:19]
	v_mfma_f32_16x16x32_bf16 v[4:7], v[160:163], v[206:209], v[4:7]
	v_mfma_f32_16x16x32_bf16 v[0:3], v[174:177], v[206:209], v[0:3]
	v_mfma_f32_16x16x32_bf16 v[52:55], v[170:173], v[186:189], v[52:55]
	v_mfma_f32_16x16x32_bf16 v[48:51], v[178:181], v[186:189], v[48:51]
	v_mfma_f32_16x16x32_bf16 v[36:39], v[170:173], v[194:197], v[36:39]
	v_mfma_f32_16x16x32_bf16 v[32:35], v[178:181], v[194:197], v[32:35]
	v_mfma_f32_16x16x32_bf16 v[20:23], v[170:173], v[202:205], v[20:23]
	v_mfma_f32_16x16x32_bf16 v[16:19], v[178:181], v[202:205], v[16:19]
	v_mfma_f32_16x16x32_bf16 v[4:7], v[170:173], v[210:213], v[4:7]
	v_mfma_f32_16x16x32_bf16 v[0:3], v[178:181], v[210:213], v[0:3]
	s_setprio 0
	s_add_i32 s91, s91, 2
	s_add_u32 s38, s38, 0x100
	s_addc_u32 s39, s39, 0
	s_add_u32 s87, s87, 0x100
	s_addc_u32 s90, s90, 0
	s_cmp_gt_u32 s91, 13
	s_barrier
	s_cbranch_scc0 .LBB0_928
	s_and_b64 vcc, exec, s[12:13]
	s_cbranch_vccz .LBB0_931
	s_barrier

; #define PG8_STAGE(bufoff, gbase, voff) do { _Pragma("unroll") for (int _i = 0; _i < 2; ++_i) \
;         __builtin_amdgcn_global_load_lds((const unsigned*)((const char*)(gbase) + (voff)[_i]), (PG8_LAS unsigned*)(lds + (bufoff) + ldsw + _i * 8192), 16, 0, 0); } while (0)
; #define PG8_LDA(dst, b, h) do { _Pragma("unroll") for (int m = 0; m < 4; ++m) _Pragma("unroll") for (int k = 0; k < 2; ++k) dst[m][k] = *(const PG8_LAS bf16x8*)(lds + PG8_SA(b, h) + aoff + m * 2048 + k * 1024); } while (0)
; #define PG8_LDB(dst, b, h) do { _Pragma("unroll") for (int n = 0; n < 2; ++n) _Pragma("unroll") for (int k = 0; k < 2; ++k) dst[n][k] = *(const PG8_LAS bf16x8*)(lds + PG8_SB(b, h) + boff + n * 2048 + k * 1024); } while (0)
; #define PG8_MMA(ai, bj, At, Bt) do { __builtin_amdgcn_s_setprio(1); _Pragma("unroll") for (int m = 0; m < 4; ++m) _Pragma("unroll") for (int n = 0; n < 2; ++n) _Pragma("unroll") for (int k = 0; k < 2; ++k) \
;         acc[ai][bj][m][n] = __builtin_amdgcn_mfma_f32_16x16x32_bf16(Bt[n][k], At[m][k], acc[ai][bj][m][n], 0, 0, 0); __builtin_amdgcn_s_setprio(0); } while (0)
; #define PG8_WAIT_V(n) asm volatile("s_waitcnt vmcnt(" #n ")" ::: "memory")
; #define PG8_WAIT_L(n) asm volatile("s_waitcnt lgkmcnt(" #n ")" ::: "memory")
; #define PG8_BAR __builtin_amdgcn_s_barrier()
; #define PG8_SCHED __builtin_amdgcn_sched_barrier(0)
; template <class Epi>
; DI void gemm_phase(PG8_LAS unsigned char* lds, const Gemm g, const StaticOrder& S, const Epi& E) {
;     ...
;         for (int t = 0; t < nt; t += 2) {
;             const bool last = (t == nt - 2);
;             const char* a1 = cA + (size_t)(t + 1) * kstep;
;             const char* a2 = last ? nA : cA + (size_t)(t + 2) * kstep; const char* b2 = last ? nB : cB + (size_t)(t + 2) * kstep;
;             const char* a3 = a2 + kstep; const char* b3 = b2 + kstep;
;             PG8_LDB(B0, 0, 0); PG8_LDB(B1, 0, 1); PG8_SCHED; PG8_LDA(At, 0, 0); PG8_STAGE(PG8_SA(1, 1), a1 + hstepA, voffA);
;             PG8_WAIT_V(8); PG8_WAIT_L(0); PG8_BAR; PG8_MMA(0, 0, At, B0); PG8_MMA(0, 1, At, B1); PG8_BAR; PG8_SCHED;
;             PG8_LDA(At, 0, 1); PG8_STAGE(PG8_SB(0, 0), b2, voffB); PG8_STAGE(PG8_SB(0, 1), b2 + hstepB, voffB); PG8_STAGE(PG8_SA(0, 0), a2, voffA);
;             PG8_WAIT_V(8); PG8_WAIT_L(0); PG8_BAR; PG8_MMA(1, 0, At, B0); PG8_MMA(1, 1, At, B1); PG8_BAR; PG8_SCHED;
.LBB0_1061:
	ds_read_b128 v[64:67], v199
	ds_read_b128 v[68:71], v199 offset:1024
	ds_read_b128 v[72:75], v199 offset:2048
	ds_read_b128 v[76:79], v199 offset:3072
	ds_read_b128 v[140:143], v200
	ds_read_b128 v[144:147], v200 offset:1024
	ds_read_b128 v[148:151], v200 offset:2048
	ds_read_b128 v[156:159], v200 offset:3072
	s_add_u32 s38, s36, 0xfffc0080
	s_addc_u32 s39, s37, -1
	s_cmp_eq_u32 s80, 12
	s_cselect_b32 s41, s5, s39
	s_cselect_b32 s40, s7, s38
	s_cselect_b32 s39, s27, s79
	s_cselect_b32 s38, s29, s78
	v_lshl_add_u64 v[194:195], s[36:37], 0, v[170:171]
	s_add_i32 m0, s44, 0xc000
	ds_read_b128 v[178:181], v201
	ds_read_b128 v[182:185], v201 offset:1024
	ds_read_b128 v[186:189], v201 offset:2048
	ds_read_b128 v[190:193], v201 offset:3072
	ds_read_b128 v[202:205], v201 offset:4096
	ds_read_b128 v[206:209], v201 offset:5120
	ds_read_b128 v[210:213], v201 offset:6144
	ds_read_b128 v[214:217], v201 offset:7168
	global_load_lds_dwordx4 v[194:195], off
	v_lshl_add_u64 v[194:195], s[36:37], 0, v[172:173]
	s_add_i32 m0, s44, 0xe000
	s_nop 0
	global_load_lds_dwordx4 v[194:195], off
	s_waitcnt vmcnt(8)
	s_waitcnt lgkmcnt(0)
	s_barrier
	s_setprio 1
	s_waitcnt lgkmcnt(0)
	v_mfma_f32_16x16x32_bf16 v[152:155], v[64:67], v[178:181], v[152:155]
	v_mfma_f32_16x16x32_bf16 v[136:139], v[72:75], v[178:181], v[136:139]
	v_mfma_f32_16x16x32_bf16 v[132:135], v[64:67], v[186:189], v[132:135]
	v_mfma_f32_16x16x32_bf16 v[128:131], v[72:75], v[186:189], v[128:131]
	v_mfma_f32_16x16x32_bf16 v[124:127], v[64:67], v[202:205], v[124:127]
	v_mfma_f32_16x16x32_bf16 v[120:123], v[72:75], v[202:205], v[120:123]
	v_mfma_f32_16x16x32_bf16 v[116:119], v[64:67], v[210:213], v[116:119]
	v_mfma_f32_16x16x32_bf16 v[112:115], v[72:75], v[210:213], v[112:115]
	v_mfma_f32_16x16x32_bf16 v[152:155], v[68:71], v[182:185], v[152:155]
	v_mfma_f32_16x16x32_bf16 v[136:139], v[76:79], v[182:185], v[136:139]
	v_mfma_f32_16x16x32_bf16 v[132:135], v[68:71], v[190:193], v[132:135]
	v_mfma_f32_16x16x32_bf16 v[128:131], v[76:79], v[190:193], v[128:131]
	v_mfma_f32_16x16x32_bf16 v[124:127], v[68:71], v[206:209], v[124:127]
	v_mfma_f32_16x16x32_bf16 v[120:123], v[76:79], v[206:209], v[120:123]
	v_mfma_f32_16x16x32_bf16 v[116:119], v[68:71], v[214:217], v[116:119]
	v_mfma_f32_16x16x32_bf16 v[112:115], v[76:79], v[214:217], v[112:115]
	s_setprio 0
	s_setprio 1
	v_mfma_f32_16x16x32_bf16 v[60:63], v[140:143], v[178:181], v[60:63]
	v_mfma_f32_16x16x32_bf16 v[56:59], v[148:151], v[178:181], v[56:59]
	v_mfma_f32_16x16x32_bf16 v[52:55], v[140:143], v[186:189], v[52:55]
	v_mfma_f32_16x16x32_bf16 v[48:51], v[148:151], v[186:189], v[48:51]
	v_mfma_f32_16x16x32_bf16 v[44:47], v[140:143], v[202:205], v[44:47]
	v_mfma_f32_16x16x32_bf16 v[40:43], v[148:151], v[202:205], v[40:43]
	v_mfma_f32_16x16x32_bf16 v[36:39], v[140:143], v[210:213], v[36:39]
	v_mfma_f32_16x16x32_bf16 v[32:35], v[148:151], v[210:213], v[32:35]
	v_mfma_f32_16x16x32_bf16 v[60:63], v[144:147], v[182:185], v[60:63]
	v_mfma_f32_16x16x32_bf16 v[56:59], v[156:159], v[182:185], v[56:59]
	v_mfma_f32_16x16x32_bf16 v[52:55], v[144:147], v[190:193], v[52:55]
	v_mfma_f32_16x16x32_bf16 v[48:51], v[156:159], v[190:193], v[48:51]
	v_mfma_f32_16x16x32_bf16 v[44:47], v[144:147], v[206:209], v[44:47]
	v_mfma_f32_16x16x32_bf16 v[40:43], v[156:159], v[206:209], v[40:43]
	v_mfma_f32_16x16x32_bf16 v[36:39], v[144:147], v[214:217], v[36:39]
	v_mfma_f32_16x16x32_bf16 v[32:35], v[156:159], v[214:217], v[32:35]
	s_setprio 0
	s_barrier
	s_add_i32 s81, s56, s43
	v_lshl_add_u64 v[194:195], s[38:39], 0, v[162:163]
	s_mov_b32 m0, s81
	ds_read_b128 v[178:181], v201 offset:16384
	ds_read_b128 v[182:185], v201 offset:17408
	ds_read_b128 v[186:189], v201 offset:18432
	ds_read_b128 v[190:193], v201 offset:19456
	ds_read_b128 v[202:205], v201 offset:20480
	ds_read_b128 v[206:209], v201 offset:21504
	ds_read_b128 v[210:213], v201 offset:22528
	ds_read_b128 v[214:217], v201 offset:23552
	global_load_lds_dwordx4 v[194:195], off
	s_add_i32 m0, s81, 0x2000
	s_add_u32 s82, s38, 0x40000
	v_lshl_add_u64 v[222:223], s[38:39], 0, v[166:167]
	s_addc_u32 s83, s39, 0
	s_add_i32 s81, s57, s43
	global_load_lds_dwordx4 v[222:223], off
	v_lshl_add_u64 v[218:219], s[82:83], 0, v[162:163]
	s_mov_b32 m0, s81
	v_lshl_add_u64 v[224:225], s[40:41], 0, v[160:161]
	global_load_lds_dwordx4 v[218:219], off
	v_lshl_add_u64 v[218:219], s[82:83], 0, v[166:167]
	s_add_i32 m0, s81, 0x2000
	v_lshl_add_u64 v[226:227], s[40:41], 0, v[164:165]
	global_load_lds_dwordx4 v[218:219], off
	s_mov_b32 m0, s44
	s_nop 0
	global_load_lds_dwordx4 v[224:225], off
	s_mov_b32 m0, s45
	s_nop 0
	global_load_lds_dwordx4 v[226:227], off
	s_waitcnt vmcnt(8)
	s_waitcnt lgkmcnt(0)
	s_barrier
; #define PG8_STAGE(bufoff, gbase, voff) do { _Pragma("unroll") for (int _i = 0; _i < 2; ++_i) \
;         __builtin_amdgcn_global_load_lds((const unsigned*)((const char*)(gbase) + (voff)[_i]), (PG8_LAS unsigned*)(lds + (bufoff) + ldsw + _i * 8192), 16, 0, 0); } while (0)
; #define PG8_LDA(dst, b, h) do { _Pragma("unroll") for (int m = 0; m < 4; ++m) _Pragma("unroll") for (int k = 0; k < 2; ++k) dst[m][k] = *(const PG8_LAS bf16x8*)(lds + PG8_SA(b, h) + aoff + m * 2048 + k * 1024); } while (0)
; #define PG8_LDB(dst, b, h) do { _Pragma("unroll") for (int n = 0; n < 2; ++n) _Pragma("unroll") for (int k = 0; k < 2; ++k) dst[n][k] = *(const PG8_LAS bf16x8*)(lds + PG8_SB(b, h) + boff + n * 2048 + k * 1024); } while (0)
; #define PG8_MMA(ai, bj, At, Bt) do { __builtin_amdgcn_s_setprio(1); _Pragma("unroll") for (int m = 0; m < 4; ++m) _Pragma("unroll") for (int n = 0; n < 2; ++n) _Pragma("unroll") for (int k = 0; k < 2; ++k) \
;         acc[ai][bj][m][n] = __builtin_amdgcn_mfma_f32_16x16x32_bf16(Bt[n][k], At[m][k], acc[ai][bj][m][n], 0, 0, 0); __builtin_amdgcn_s_setprio(0); } while (0)
; #define PG8_WAIT_V(n) asm volatile("s_waitcnt vmcnt(" #n ")" ::: "memory")
; #define PG8_WAIT_L(n) asm volatile("s_waitcnt lgkmcnt(" #n ")" ::: "memory")
; #define PG8_BAR __builtin_amdgcn_s_barrier()
; #define PG8_SCHED __builtin_amdgcn_sched_barrier(0)
; template <class Epi>
; DI void gemm_phase(PG8_LAS unsigned char* lds, const Gemm g, const StaticOrder& S, const Epi& E) {
;     ...
;             PG8_WAIT_V(8); PG8_WAIT_L(0); PG8_BAR; PG8_MMA(1, 0, At, B0); PG8_MMA(1, 1, At, B1); PG8_BAR; PG8_SCHED;
;             PG8_LDB(B0, 1, 0); PG8_LDB(B1, 1, 1); PG8_SCHED; PG8_LDA(At, 1, 0); PG8_STAGE(PG8_SA(0, 1), a2 + hstepA, voffA);
;             PG8_WAIT_V(8); PG8_WAIT_L(0); PG8_BAR; PG8_MMA(0, 0, At, B0); PG8_MMA(0, 1, At, B1); PG8_BAR; PG8_SCHED;
;             PG8_LDA(At, 1, 1); PG8_STAGE(PG8_SB(1, 0), b3, voffB); PG8_STAGE(PG8_SB(1, 1), b3 + hstepB, voffB); PG8_STAGE(PG8_SA(1, 0), a3, voffA);
	s_setprio 1
	s_waitcnt lgkmcnt(0)
	v_mfma_f32_16x16x32_bf16 v[108:111], v[64:67], v[178:181], v[108:111]
	v_mfma_f32_16x16x32_bf16 v[104:107], v[72:75], v[178:181], v[104:107]
	v_mfma_f32_16x16x32_bf16 v[100:103], v[64:67], v[186:189], v[100:103]
	v_mfma_f32_16x16x32_bf16 v[96:99], v[72:75], v[186:189], v[96:99]
	v_mfma_f32_16x16x32_bf16 v[92:95], v[64:67], v[202:205], v[92:95]
	v_mfma_f32_16x16x32_bf16 v[88:91], v[72:75], v[202:205], v[88:91]
	v_mfma_f32_16x16x32_bf16 v[64:67], v[64:67], v[210:213], v[84:87]
	v_mfma_f32_16x16x32_bf16 v[108:111], v[68:71], v[182:185], v[108:111]
	v_mfma_f32_16x16x32_bf16 v[104:107], v[76:79], v[182:185], v[104:107]
	v_mfma_f32_16x16x32_bf16 v[100:103], v[68:71], v[190:193], v[100:103]
	v_mfma_f32_16x16x32_bf16 v[96:99], v[76:79], v[190:193], v[96:99]
	v_mfma_f32_16x16x32_bf16 v[92:95], v[68:71], v[206:209], v[92:95]
	v_mfma_f32_16x16x32_bf16 v[88:91], v[76:79], v[206:209], v[88:91]
	v_mfma_f32_16x16x32_bf16 v[64:67], v[68:71], v[214:217], v[64:67]
	v_mfma_f32_16x16x32_bf16 v[68:71], v[72:75], v[210:213], v[80:83]
	v_mfma_f32_16x16x32_bf16 v[68:71], v[76:79], v[214:217], v[68:71]
	s_setprio 0
	s_setprio 1
	v_mfma_f32_16x16x32_bf16 v[28:31], v[140:143], v[178:181], v[28:31]
	v_mfma_f32_16x16x32_bf16 v[24:27], v[148:151], v[178:181], v[24:27]
	v_mfma_f32_16x16x32_bf16 v[20:23], v[140:143], v[186:189], v[20:23]
	v_mfma_f32_16x16x32_bf16 v[16:19], v[148:151], v[186:189], v[16:19]
	v_mfma_f32_16x16x32_bf16 v[12:15], v[140:143], v[202:205], v[12:15]
	v_mfma_f32_16x16x32_bf16 v[8:11], v[148:151], v[202:205], v[8:11]
	v_mfma_f32_16x16x32_bf16 v[4:7], v[140:143], v[210:213], v[4:7]
	v_mfma_f32_16x16x32_bf16 v[0:3], v[148:151], v[210:213], v[0:3]
	v_mfma_f32_16x16x32_bf16 v[28:31], v[144:147], v[182:185], v[28:31]
	v_mfma_f32_16x16x32_bf16 v[24:27], v[156:159], v[182:185], v[24:27]
	v_mfma_f32_16x16x32_bf16 v[20:23], v[144:147], v[190:193], v[20:23]
	v_mfma_f32_16x16x32_bf16 v[16:19], v[156:159], v[190:193], v[16:19]
	v_mfma_f32_16x16x32_bf16 v[12:15], v[144:147], v[206:209], v[12:15]
	v_mfma_f32_16x16x32_bf16 v[8:11], v[156:159], v[206:209], v[8:11]
	v_mfma_f32_16x16x32_bf16 v[4:7], v[144:147], v[214:217], v[4:7]
	v_mfma_f32_16x16x32_bf16 v[0:3], v[156:159], v[214:217], v[0:3]
	s_setprio 0
	s_barrier
	s_add_i32 s81, 16, 0x18000
	v_add_u32_e32 v84, s81, v198
	s_add_i32 s82, 16, 0x1c000
	ds_read_b128 v[72:75], v84
	ds_read_b128 v[76:79], v84 offset:1024
	ds_read_b128 v[80:83], v84 offset:2048
	ds_read_b128 v[140:143], v84 offset:3072
	v_add_u32_e32 v84, s82, v198
	ds_read_b128 v[144:147], v84
	ds_read_b128 v[148:151], v84 offset:1024
	ds_read_b128 v[156:159], v84 offset:2048
	ds_read_b128 v[178:181], v84 offset:3072
	s_add_u32 s40, s40, 0x40000
	s_addc_u32 s41, s41, 0
	s_mov_b32 m0, s46
	v_lshl_add_u64 v[218:219], s[40:41], 0, v[160:161]
	ds_read_b128 v[84:87], v201 offset:32768
	ds_read_b128 v[182:185], v201 offset:33792
	ds_read_b128 v[186:189], v201 offset:34816
	ds_read_b128 v[190:193], v201 offset:35840
	ds_read_b128 v[202:205], v201 offset:36864
	ds_read_b128 v[206:209], v201 offset:37888
	ds_read_b128 v[210:213], v201 offset:38912
	ds_read_b128 v[214:217], v201 offset:39936
	global_load_lds_dwordx4 v[218:219], off
	v_lshl_add_u64 v[218:219], s[40:41], 0, v[164:165]
	s_mov_b32 m0, s47
	s_nop 0
	global_load_lds_dwordx4 v[218:219], off
	s_waitcnt vmcnt(8)
	s_waitcnt lgkmcnt(0)
	s_barrier
	s_setprio 1
	s_waitcnt lgkmcnt(0)
	v_mfma_f32_16x16x32_bf16 v[152:155], v[72:75], v[84:87], v[152:155]
	v_mfma_f32_16x16x32_bf16 v[136:139], v[80:83], v[84:87], v[136:139]
	v_mfma_f32_16x16x32_bf16 v[132:135], v[72:75], v[186:189], v[132:135]
	v_mfma_f32_16x16x32_bf16 v[128:131], v[80:83], v[186:189], v[128:131]
	v_mfma_f32_16x16x32_bf16 v[124:127], v[72:75], v[202:205], v[124:127]
	v_mfma_f32_16x16x32_bf16 v[120:123], v[80:83], v[202:205], v[120:123]
	v_mfma_f32_16x16x32_bf16 v[116:119], v[72:75], v[210:213], v[116:119]
	v_mfma_f32_16x16x32_bf16 v[112:115], v[80:83], v[210:213], v[112:115]
	v_mfma_f32_16x16x32_bf16 v[152:155], v[76:79], v[182:185], v[152:155]
	v_mfma_f32_16x16x32_bf16 v[136:139], v[140:143], v[182:185], v[136:139]
	v_mfma_f32_16x16x32_bf16 v[132:135], v[76:79], v[190:193], v[132:135]
	v_mfma_f32_16x16x32_bf16 v[128:131], v[140:143], v[190:193], v[128:131]
	v_mfma_f32_16x16x32_bf16 v[124:127], v[76:79], v[206:209], v[124:127]
	v_mfma_f32_16x16x32_bf16 v[120:123], v[140:143], v[206:209], v[120:123]
	v_mfma_f32_16x16x32_bf16 v[116:119], v[76:79], v[214:217], v[116:119]
	v_mfma_f32_16x16x32_bf16 v[112:115], v[140:143], v[214:217], v[112:115]
	s_setprio 0
	s_setprio 1
	v_mfma_f32_16x16x32_bf16 v[60:63], v[144:147], v[84:87], v[60:63]
	v_mfma_f32_16x16x32_bf16 v[56:59], v[156:159], v[84:87], v[56:59]
	v_mfma_f32_16x16x32_bf16 v[52:55], v[144:147], v[186:189], v[52:55]
	v_mfma_f32_16x16x32_bf16 v[48:51], v[156:159], v[186:189], v[48:51]
	v_mfma_f32_16x16x32_bf16 v[44:47], v[144:147], v[202:205], v[44:47]
	v_mfma_f32_16x16x32_bf16 v[40:43], v[156:159], v[202:205], v[40:43]
	v_mfma_f32_16x16x32_bf16 v[36:39], v[144:147], v[210:213], v[36:39]
	v_mfma_f32_16x16x32_bf16 v[32:35], v[156:159], v[210:213], v[32:35]
	v_mfma_f32_16x16x32_bf16 v[60:63], v[148:151], v[182:185], v[60:63]
	v_mfma_f32_16x16x32_bf16 v[56:59], v[178:181], v[182:185], v[56:59]
	v_mfma_f32_16x16x32_bf16 v[52:55], v[148:151], v[190:193], v[52:55]
	v_mfma_f32_16x16x32_bf16 v[48:51], v[178:181], v[190:193], v[48:51]
	v_mfma_f32_16x16x32_bf16 v[44:47], v[148:151], v[206:209], v[44:47]
	v_mfma_f32_16x16x32_bf16 v[40:43], v[178:181], v[206:209], v[40:43]
	v_mfma_f32_16x16x32_bf16 v[36:39], v[148:151], v[214:217], v[36:39]
	v_mfma_f32_16x16x32_bf16 v[32:35], v[178:181], v[214:217], v[32:35]
	s_setprio 0
	s_barrier
; #define PG8_STAGE(bufoff, gbase, voff) do { _Pragma("unroll") for (int _i = 0; _i < 2; ++_i) \
;         __builtin_amdgcn_global_load_lds((const unsigned*)((const char*)(gbase) + (voff)[_i]), (PG8_LAS unsigned*)(lds + (bufoff) + ldsw + _i * 8192), 16, 0, 0); } while (0)
; #define PG8_LDA(dst, b, h) do { _Pragma("unroll") for (int m = 0; m < 4; ++m) _Pragma("unroll") for (int k = 0; k < 2; ++k) dst[m][k] = *(const PG8_LAS bf16x8*)(lds + PG8_SA(b, h) + aoff + m * 2048 + k * 1024); } while (0)
; #define PG8_MMA(ai, bj, At, Bt) do { __builtin_amdgcn_s_setprio(1); _Pragma("unroll") for (int m = 0; m < 4; ++m) _Pragma("unroll") for (int n = 0; n < 2; ++n) _Pragma("unroll") for (int k = 0; k < 2; ++k) \
;         acc[ai][bj][m][n] = __builtin_amdgcn_mfma_f32_16x16x32_bf16(Bt[n][k], At[m][k], acc[ai][bj][m][n], 0, 0, 0); __builtin_amdgcn_s_setprio(0); } while (0)
; #define PG8_WAIT_V(n) asm volatile("s_waitcnt vmcnt(" #n ")" ::: "memory")
; #define PG8_WAIT_L(n) asm volatile("s_waitcnt lgkmcnt(" #n ")" ::: "memory")
; #define PG8_BAR __builtin_amdgcn_s_barrier()
; #define PG8_SCHED __builtin_amdgcn_sched_barrier(0)
; template <class Epi>
; DI void gemm_phase(PG8_LAS unsigned char* lds, const Gemm g, const StaticOrder& S, const Epi& E) {
;     ...
;         for (int t = 0; t < nt; t += 2) {
;     ...
;             PG8_LDA(At, 1, 1); PG8_STAGE(PG8_SB(1, 0), b3, voffB); PG8_STAGE(PG8_SB(1, 1), b3 + hstepB, voffB); PG8_STAGE(PG8_SA(1, 0), a3, voffA);
;             PG8_WAIT_V(8); PG8_WAIT_L(0); PG8_BAR; PG8_MMA(1, 0, At, B0); PG8_MMA(1, 1, At, B1); PG8_BAR; PG8_SCHED;
;         }
	s_add_i32 s40, s81, s43
	v_lshl_add_u64 v[84:85], v[194:195], 0, s[18:19]
	s_mov_b32 m0, s40
	ds_read_b128 v[182:185], v201 offset:49152
	ds_read_b128 v[186:189], v201 offset:50176
	ds_read_b128 v[190:193], v201 offset:51200
	ds_read_b128 v[202:205], v201 offset:52224
	ds_read_b128 v[206:209], v201 offset:53248
	ds_read_b128 v[210:213], v201 offset:54272
	ds_read_b128 v[214:217], v201 offset:55296
	ds_read_b128 v[218:221], v201 offset:56320
	global_load_lds_dwordx4 v[84:85], off
	s_add_i32 m0, s40, 0x2000
	s_add_u32 s38, s38, 0x40080
	v_lshl_add_u64 v[84:85], v[222:223], 0, s[18:19]
	s_addc_u32 s39, s39, 0
	s_add_i32 s40, s82, s43
	global_load_lds_dwordx4 v[84:85], off
	v_lshl_add_u64 v[84:85], s[38:39], 0, v[162:163]
	s_mov_b32 m0, s40
	s_nop 0
	global_load_lds_dwordx4 v[84:85], off
	v_lshl_add_u64 v[84:85], s[38:39], 0, v[166:167]
	s_add_i32 m0, s40, 0x2000
	s_nop 0
	global_load_lds_dwordx4 v[84:85], off
	v_lshl_add_u64 v[84:85], v[224:225], 0, s[18:19]
	s_mov_b32 m0, s50
	s_nop 0
	global_load_lds_dwordx4 v[84:85], off
	v_lshl_add_u64 v[84:85], v[226:227], 0, s[18:19]
	s_mov_b32 m0, s51
	s_nop 0
	global_load_lds_dwordx4 v[84:85], off
	s_waitcnt vmcnt(8)
	s_waitcnt lgkmcnt(0)
	s_barrier
	s_setprio 1
	s_waitcnt lgkmcnt(0)
	v_mfma_f32_16x16x32_bf16 v[84:87], v[72:75], v[182:185], v[108:111]
	v_mfma_f32_16x16x32_bf16 v[108:111], v[76:79], v[186:189], v[84:87]
	v_mfma_f32_16x16x32_bf16 v[84:87], v[80:83], v[182:185], v[104:107]
	v_mfma_f32_16x16x32_bf16 v[104:107], v[140:143], v[186:189], v[84:87]
	v_mfma_f32_16x16x32_bf16 v[84:87], v[72:75], v[190:193], v[100:103]
	v_mfma_f32_16x16x32_bf16 v[100:103], v[76:79], v[202:205], v[84:87]
	v_mfma_f32_16x16x32_bf16 v[84:87], v[80:83], v[190:193], v[96:99]
	v_mfma_f32_16x16x32_bf16 v[96:99], v[140:143], v[202:205], v[84:87]
	v_mfma_f32_16x16x32_bf16 v[84:87], v[72:75], v[206:209], v[92:95]
	v_mfma_f32_16x16x32_bf16 v[92:95], v[76:79], v[210:213], v[84:87]
	v_mfma_f32_16x16x32_bf16 v[84:87], v[80:83], v[206:209], v[88:91]
	v_mfma_f32_16x16x32_bf16 v[64:67], v[72:75], v[214:217], v[64:67]
	v_mfma_f32_16x16x32_bf16 v[88:91], v[140:143], v[210:213], v[84:87]
	v_mfma_f32_16x16x32_bf16 v[84:87], v[76:79], v[218:221], v[64:67]
	v_mfma_f32_16x16x32_bf16 v[64:67], v[80:83], v[214:217], v[68:71]
	v_mfma_f32_16x16x32_bf16 v[80:83], v[140:143], v[218:221], v[64:67]
	s_setprio 0
	s_setprio 1
	v_mfma_f32_16x16x32_bf16 v[28:31], v[144:147], v[182:185], v[28:31]
	v_mfma_f32_16x16x32_bf16 v[24:27], v[156:159], v[182:185], v[24:27]
	v_mfma_f32_16x16x32_bf16 v[20:23], v[144:147], v[190:193], v[20:23]
	v_mfma_f32_16x16x32_bf16 v[16:19], v[156:159], v[190:193], v[16:19]
	v_mfma_f32_16x16x32_bf16 v[12:15], v[144:147], v[206:209], v[12:15]
	v_mfma_f32_16x16x32_bf16 v[8:11], v[156:159], v[206:209], v[8:11]
	v_mfma_f32_16x16x32_bf16 v[4:7], v[144:147], v[214:217], v[4:7]
	v_mfma_f32_16x16x32_bf16 v[0:3], v[156:159], v[214:217], v[0:3]
	v_mfma_f32_16x16x32_bf16 v[28:31], v[148:151], v[186:189], v[28:31]
	v_mfma_f32_16x16x32_bf16 v[24:27], v[178:181], v[186:189], v[24:27]
	v_mfma_f32_16x16x32_bf16 v[20:23], v[148:151], v[202:205], v[20:23]
	v_mfma_f32_16x16x32_bf16 v[16:19], v[178:181], v[202:205], v[16:19]
	v_mfma_f32_16x16x32_bf16 v[12:15], v[148:151], v[210:213], v[12:15]
	v_mfma_f32_16x16x32_bf16 v[8:11], v[178:181], v[210:213], v[8:11]
	v_mfma_f32_16x16x32_bf16 v[4:7], v[148:151], v[218:221], v[4:7]
	v_mfma_f32_16x16x32_bf16 v[0:3], v[178:181], v[218:221], v[0:3]
	s_setprio 0
	s_add_i32 s80, s80, 2
	s_add_u32 s36, s36, 0x100
	s_addc_u32 s37, s37, 0
	s_add_u32 s78, s78, 0x100
	s_addc_u32 s79, s79, 0
	s_cmp_gt_u32 s80, 13
	s_barrier
	s_cbranch_scc0 .LBB0_1061
	s_and_b64 vcc, exec, s[20:21]
	s_cbranch_vccz .LBB0_1064
	s_barrier

; #define PG8_STAGE(bufoff, gbase, voff) do { _Pragma("unroll") for (int _i = 0; _i < 2; ++_i) \
;         __builtin_amdgcn_global_load_lds((const unsigned*)((const char*)(gbase) + (voff)[_i]), (PG8_LAS unsigned*)(lds + (bufoff) + ldsw + _i * 8192), 16, 0, 0); } while (0)
; #define PG8_LDA(dst, b, h) do { _Pragma("unroll") for (int m = 0; m < 4; ++m) _Pragma("unroll") for (int k = 0; k < 2; ++k) dst[m][k] = *(const PG8_LAS bf16x8*)(lds + PG8_SA(b, h) + aoff + m * 2048 + k * 1024); } while (0)
; #define PG8_LDB(dst, b, h) do { _Pragma("unroll") for (int n = 0; n < 2; ++n) _Pragma("unroll") for (int k = 0; k < 2; ++k) dst[n][k] = *(const PG8_LAS bf16x8*)(lds + PG8_SB(b, h) + boff + n * 2048 + k * 1024); } while (0)
; #define PG8_MMA(ai, bj, At, Bt) do { __builtin_amdgcn_s_setprio(1); _Pragma("unroll") for (int m = 0; m < 4; ++m) _Pragma("unroll") for (int n = 0; n < 2; ++n) _Pragma("unroll") for (int k = 0; k < 2; ++k) \
;         acc[ai][bj][m][n] = __builtin_amdgcn_mfma_f32_16x16x32_bf16(Bt[n][k], At[m][k], acc[ai][bj][m][n], 0, 0, 0); __builtin_amdgcn_s_setprio(0); } while (0)
; #define PG8_WAIT_V(n) asm volatile("s_waitcnt vmcnt(" #n ")" ::: "memory")
; #define PG8_WAIT_L(n) asm volatile("s_waitcnt lgkmcnt(" #n ")" ::: "memory")
; #define PG8_BAR __builtin_amdgcn_s_barrier()
; #define PG8_SCHED __builtin_amdgcn_sched_barrier(0)
; template <class Epi>
; DI void gemm_phase(PG8_LAS unsigned char* lds, const Gemm g, const StaticOrder& S, const Epi& E) {
;     ...
;             PG8_LDB(B0, 0, 0); PG8_LDB(B1, 0, 1); PG8_SCHED; PG8_LDA(At, 0, 0); PG8_STAGE(PG8_SA(1, 1), a1 + hstepA, voffA);
;             PG8_WAIT_V(8); PG8_WAIT_L(0); PG8_BAR; PG8_MMA(0, 0, At, B0); PG8_MMA(0, 1, At, B1); PG8_BAR; PG8_SCHED;
;             PG8_LDA(At, 0, 1); PG8_STAGE(PG8_SB(0, 0), b2, voffB); PG8_STAGE(PG8_SB(0, 1), b2 + hstepB, voffB); PG8_STAGE(PG8_SA(0, 0), a2, voffA);
;             PG8_WAIT_V(8); PG8_WAIT_L(0); PG8_BAR; PG8_MMA(1, 0, At, B0); PG8_MMA(1, 1, At, B1); PG8_BAR; PG8_SCHED;
;             PG8_LDB(B0, 1, 0); PG8_LDB(B1, 1, 1); PG8_SCHED; PG8_LDA(At, 1, 0); PG8_STAGE(PG8_SA(0, 1), a2 + hstepA, voffA);
.LBB0_1224:
	ds_read_b128 v[144:147], v211
	ds_read_b128 v[148:151], v211 offset:1024
	ds_read_b128 v[152:155], v211 offset:2048
	ds_read_b128 v[156:159], v211 offset:3072
	ds_read_b128 v[160:163], v212
	ds_read_b128 v[164:167], v212 offset:1024
	ds_read_b128 v[168:171], v212 offset:2048
	ds_read_b128 v[172:175], v212 offset:3072
	s_add_u32 s22, s20, 0x100
	s_addc_u32 s23, s21, 0
	s_cmp_eq_u32 s57, 40
	s_cselect_b32 s27, s5, s23
	s_cselect_b32 s26, s4, s22
	s_cselect_b32 s25, s19, s56
	s_cselect_b32 s24, s18, s55
	v_lshl_add_u64 v[214:215], s[20:21], 0, v[136:137]
	s_add_i32 m0, s30, 0xc000
	ds_read_b128 v[176:179], v213
	ds_read_b128 v[180:183], v213 offset:1024
	ds_read_b128 v[184:187], v213 offset:2048
	ds_read_b128 v[188:191], v213 offset:3072
	ds_read_b128 v[192:195], v213 offset:4096
	ds_read_b128 v[196:199], v213 offset:5120
	ds_read_b128 v[200:203], v213 offset:6144
	ds_read_b128 v[204:207], v213 offset:7168
	global_load_lds_dwordx4 v[214:215], off
	v_lshl_add_u64 v[214:215], s[20:21], 0, v[138:139]
	s_add_i32 m0, s30, 0xe000
	s_nop 0
	global_load_lds_dwordx4 v[214:215], off
	s_waitcnt vmcnt(8)
	s_waitcnt lgkmcnt(0)
	s_barrier
	s_setprio 1
	s_waitcnt lgkmcnt(0)
	v_mfma_f32_16x16x32_bf16 v[124:127], v[144:147], v[176:179], v[124:127]
	v_mfma_f32_16x16x32_bf16 v[120:123], v[152:155], v[176:179], v[120:123]
	v_mfma_f32_16x16x32_bf16 v[108:111], v[144:147], v[184:187], v[108:111]
	v_mfma_f32_16x16x32_bf16 v[104:107], v[152:155], v[184:187], v[104:107]
	v_mfma_f32_16x16x32_bf16 v[92:95], v[144:147], v[192:195], v[92:95]
	v_mfma_f32_16x16x32_bf16 v[88:91], v[152:155], v[192:195], v[88:91]
	v_mfma_f32_16x16x32_bf16 v[76:79], v[144:147], v[200:203], v[76:79]
	v_mfma_f32_16x16x32_bf16 v[72:75], v[152:155], v[200:203], v[72:75]
	v_mfma_f32_16x16x32_bf16 v[124:127], v[148:151], v[180:183], v[124:127]
	v_mfma_f32_16x16x32_bf16 v[120:123], v[156:159], v[180:183], v[120:123]
	v_mfma_f32_16x16x32_bf16 v[108:111], v[148:151], v[188:191], v[108:111]
	v_mfma_f32_16x16x32_bf16 v[104:107], v[156:159], v[188:191], v[104:107]
	v_mfma_f32_16x16x32_bf16 v[92:95], v[148:151], v[196:199], v[92:95]
	v_mfma_f32_16x16x32_bf16 v[88:91], v[156:159], v[196:199], v[88:91]
	v_mfma_f32_16x16x32_bf16 v[76:79], v[148:151], v[204:207], v[76:79]
	v_mfma_f32_16x16x32_bf16 v[72:75], v[156:159], v[204:207], v[72:75]
	s_setprio 0
	s_setprio 1
	v_mfma_f32_16x16x32_bf16 v[116:119], v[160:163], v[176:179], v[116:119]
	v_mfma_f32_16x16x32_bf16 v[112:115], v[168:171], v[176:179], v[112:115]
	v_mfma_f32_16x16x32_bf16 v[100:103], v[160:163], v[184:187], v[100:103]
	v_mfma_f32_16x16x32_bf16 v[96:99], v[168:171], v[184:187], v[96:99]
	v_mfma_f32_16x16x32_bf16 v[84:87], v[160:163], v[192:195], v[84:87]
	v_mfma_f32_16x16x32_bf16 v[80:83], v[168:171], v[192:195], v[80:83]
	v_mfma_f32_16x16x32_bf16 v[68:71], v[160:163], v[200:203], v[68:71]
	v_mfma_f32_16x16x32_bf16 v[64:67], v[168:171], v[200:203], v[64:67]
	v_mfma_f32_16x16x32_bf16 v[116:119], v[164:167], v[180:183], v[116:119]
	v_mfma_f32_16x16x32_bf16 v[112:115], v[172:175], v[180:183], v[112:115]
	v_mfma_f32_16x16x32_bf16 v[100:103], v[164:167], v[188:191], v[100:103]
	v_mfma_f32_16x16x32_bf16 v[96:99], v[172:175], v[188:191], v[96:99]
	v_mfma_f32_16x16x32_bf16 v[84:87], v[164:167], v[196:199], v[84:87]
	v_mfma_f32_16x16x32_bf16 v[80:83], v[172:175], v[196:199], v[80:83]
	v_mfma_f32_16x16x32_bf16 v[68:71], v[164:167], v[204:207], v[68:71]
	v_mfma_f32_16x16x32_bf16 v[64:67], v[172:175], v[204:207], v[64:67]
	s_setprio 0
	s_barrier
	s_add_i32 s20, s45, s29
	v_lshl_add_u64 v[214:215], s[24:25], 0, v[130:131]
	s_mov_b32 m0, s20
	ds_read_b128 v[176:179], v213 offset:16384
	ds_read_b128 v[180:183], v213 offset:17408
	ds_read_b128 v[184:187], v213 offset:18432
	ds_read_b128 v[188:191], v213 offset:19456
	ds_read_b128 v[192:195], v213 offset:20480
	ds_read_b128 v[196:199], v213 offset:21504
	ds_read_b128 v[200:203], v213 offset:22528
	ds_read_b128 v[204:207], v213 offset:23552
	global_load_lds_dwordx4 v[214:215], off
	s_add_i32 m0, s20, 0x2000
	s_add_u32 s20, s24, 0xb0000
	v_lshl_add_u64 v[216:217], s[24:25], 0, v[134:135]
	s_addc_u32 s21, s25, 0
	s_add_i32 s58, s46, s29
	global_load_lds_dwordx4 v[216:217], off
	v_lshl_add_u64 v[218:219], s[20:21], 0, v[130:131]
	s_mov_b32 m0, s58
	v_lshl_add_u64 v[220:221], s[26:27], 0, v[132:133]
	global_load_lds_dwordx4 v[218:219], off
	v_lshl_add_u64 v[218:219], s[20:21], 0, v[134:135]
	s_add_i32 m0, s58, 0x2000
	s_nop 0
	global_load_lds_dwordx4 v[218:219], off
	v_lshl_add_u64 v[218:219], s[26:27], 0, v[128:129]
	s_mov_b32 m0, s30
	s_nop 0
	global_load_lds_dwordx4 v[218:219], off
	s_mov_b32 m0, s31
	s_nop 0
	global_load_lds_dwordx4 v[220:221], off
	s_waitcnt vmcnt(8)
	s_waitcnt lgkmcnt(0)
	s_barrier
; #define PG8_STAGE(bufoff, gbase, voff) do { _Pragma("unroll") for (int _i = 0; _i < 2; ++_i) \
;         __builtin_amdgcn_global_load_lds((const unsigned*)((const char*)(gbase) + (voff)[_i]), (PG8_LAS unsigned*)(lds + (bufoff) + ldsw + _i * 8192), 16, 0, 0); } while (0)
; #define PG8_LDA(dst, b, h) do { _Pragma("unroll") for (int m = 0; m < 4; ++m) _Pragma("unroll") for (int k = 0; k < 2; ++k) dst[m][k] = *(const PG8_LAS bf16x8*)(lds + PG8_SA(b, h) + aoff + m * 2048 + k * 1024); } while (0)
; #define PG8_LDB(dst, b, h) do { _Pragma("unroll") for (int n = 0; n < 2; ++n) _Pragma("unroll") for (int k = 0; k < 2; ++k) dst[n][k] = *(const PG8_LAS bf16x8*)(lds + PG8_SB(b, h) + boff + n * 2048 + k * 1024); } while (0)
; #define PG8_MMA(ai, bj, At, Bt) do { __builtin_amdgcn_s_setprio(1); _Pragma("unroll") for (int m = 0; m < 4; ++m) _Pragma("unroll") for (int n = 0; n < 2; ++n) _Pragma("unroll") for (int k = 0; k < 2; ++k) \
;         acc[ai][bj][m][n] = __builtin_amdgcn_mfma_f32_16x16x32_bf16(Bt[n][k], At[m][k], acc[ai][bj][m][n], 0, 0, 0); __builtin_amdgcn_s_setprio(0); } while (0)
; #define PG8_WAIT_V(n) asm volatile("s_waitcnt vmcnt(" #n ")" ::: "memory")
; #define PG8_WAIT_L(n) asm volatile("s_waitcnt lgkmcnt(" #n ")" ::: "memory")
; #define PG8_BAR __builtin_amdgcn_s_barrier()
; #define PG8_SCHED __builtin_amdgcn_sched_barrier(0)
; template <class Epi>
; DI void gemm_phase(PG8_LAS unsigned char* lds, const Gemm g, const StaticOrder& S, const Epi& E) {
;     ...
;             PG8_WAIT_V(8); PG8_WAIT_L(0); PG8_BAR; PG8_MMA(1, 0, At, B0); PG8_MMA(1, 1, At, B1); PG8_BAR; PG8_SCHED;
;             PG8_LDB(B0, 1, 0); PG8_LDB(B1, 1, 1); PG8_SCHED; PG8_LDA(At, 1, 0); PG8_STAGE(PG8_SA(0, 1), a2 + hstepA, voffA);
;             PG8_WAIT_V(8); PG8_WAIT_L(0); PG8_BAR; PG8_MMA(0, 0, At, B0); PG8_MMA(0, 1, At, B1); PG8_BAR; PG8_SCHED;
;             PG8_LDA(At, 1, 1); PG8_STAGE(PG8_SB(1, 0), b3, voffB); PG8_STAGE(PG8_SB(1, 1), b3 + hstepB, voffB); PG8_STAGE(PG8_SA(1, 0), a3, voffA);
	s_setprio 1
	s_waitcnt lgkmcnt(0)
	v_mfma_f32_16x16x32_bf16 v[60:63], v[144:147], v[176:179], v[60:63]
	v_mfma_f32_16x16x32_bf16 v[56:59], v[152:155], v[176:179], v[56:59]
	v_mfma_f32_16x16x32_bf16 v[44:47], v[144:147], v[184:187], v[44:47]
	v_mfma_f32_16x16x32_bf16 v[40:43], v[152:155], v[184:187], v[40:43]
	v_mfma_f32_16x16x32_bf16 v[32:35], v[144:147], v[192:195], v[32:35]
	v_mfma_f32_16x16x32_bf16 v[24:27], v[152:155], v[192:195], v[24:27]
	v_mfma_f32_16x16x32_bf16 v[12:15], v[144:147], v[200:203], v[12:15]
	v_mfma_f32_16x16x32_bf16 v[8:11], v[152:155], v[200:203], v[8:11]
	v_mfma_f32_16x16x32_bf16 v[60:63], v[148:151], v[180:183], v[60:63]
	v_mfma_f32_16x16x32_bf16 v[56:59], v[156:159], v[180:183], v[56:59]
	v_mfma_f32_16x16x32_bf16 v[44:47], v[148:151], v[188:191], v[44:47]
	v_mfma_f32_16x16x32_bf16 v[40:43], v[156:159], v[188:191], v[40:43]
	v_mfma_f32_16x16x32_bf16 v[32:35], v[148:151], v[196:199], v[32:35]
	v_mfma_f32_16x16x32_bf16 v[24:27], v[156:159], v[196:199], v[24:27]
	v_mfma_f32_16x16x32_bf16 v[12:15], v[148:151], v[204:207], v[12:15]
	v_mfma_f32_16x16x32_bf16 v[8:11], v[156:159], v[204:207], v[8:11]
	s_setprio 0
	s_setprio 1
	v_mfma_f32_16x16x32_bf16 v[52:55], v[160:163], v[176:179], v[52:55]
	v_mfma_f32_16x16x32_bf16 v[48:51], v[168:171], v[176:179], v[48:51]
	v_mfma_f32_16x16x32_bf16 v[36:39], v[160:163], v[184:187], v[36:39]
	v_mfma_f32_16x16x32_bf16 v[28:31], v[168:171], v[184:187], v[28:31]
	v_mfma_f32_16x16x32_bf16 v[20:23], v[160:163], v[192:195], v[20:23]
	v_mfma_f32_16x16x32_bf16 v[16:19], v[168:171], v[192:195], v[16:19]
	v_mfma_f32_16x16x32_bf16 v[4:7], v[160:163], v[200:203], v[4:7]
	v_mfma_f32_16x16x32_bf16 v[0:3], v[168:171], v[200:203], v[0:3]
	v_mfma_f32_16x16x32_bf16 v[52:55], v[164:167], v[180:183], v[52:55]
	v_mfma_f32_16x16x32_bf16 v[48:51], v[172:175], v[180:183], v[48:51]
	v_mfma_f32_16x16x32_bf16 v[36:39], v[164:167], v[188:191], v[36:39]
	v_mfma_f32_16x16x32_bf16 v[28:31], v[172:175], v[188:191], v[28:31]
	v_mfma_f32_16x16x32_bf16 v[20:23], v[164:167], v[196:199], v[20:23]
	v_mfma_f32_16x16x32_bf16 v[16:19], v[172:175], v[196:199], v[16:19]
	v_mfma_f32_16x16x32_bf16 v[4:7], v[164:167], v[204:207], v[4:7]
	v_mfma_f32_16x16x32_bf16 v[0:3], v[172:175], v[204:207], v[0:3]
	s_setprio 0
	s_barrier
	s_add_i32 s58, 16, 0x18000
	s_add_i32 s59, 16, 0x1c000
	v_add_u32_e32 v156, s58, v210
	v_add_u32_e32 v172, s59, v210
	ds_read_b128 v[144:147], v156
	ds_read_b128 v[148:151], v156 offset:1024
	ds_read_b128 v[152:155], v156 offset:2048
	ds_read_b128 v[156:159], v156 offset:3072
	ds_read_b128 v[160:163], v172
	ds_read_b128 v[164:167], v172 offset:1024
	ds_read_b128 v[168:171], v172 offset:2048
	ds_read_b128 v[172:175], v172 offset:3072
	s_add_u32 s20, s26, 0xb0000
	s_addc_u32 s21, s27, 0
	s_mov_b32 m0, s34
	v_lshl_add_u64 v[222:223], s[20:21], 0, v[128:129]
	ds_read_b128 v[176:179], v213 offset:32768
	ds_read_b128 v[180:183], v213 offset:33792
	ds_read_b128 v[184:187], v213 offset:34816
	ds_read_b128 v[188:191], v213 offset:35840
	ds_read_b128 v[192:195], v213 offset:36864
	ds_read_b128 v[196:199], v213 offset:37888
	ds_read_b128 v[200:203], v213 offset:38912
	ds_read_b128 v[204:207], v213 offset:39936
	global_load_lds_dwordx4 v[222:223], off
	v_lshl_add_u64 v[222:223], s[20:21], 0, v[132:133]
	s_mov_b32 m0, s35
	s_nop 0
	global_load_lds_dwordx4 v[222:223], off
	s_waitcnt vmcnt(8)
	s_waitcnt lgkmcnt(0)
	s_barrier
	s_setprio 1
	s_waitcnt lgkmcnt(0)
	v_mfma_f32_16x16x32_bf16 v[124:127], v[144:147], v[176:179], v[124:127]
	v_mfma_f32_16x16x32_bf16 v[120:123], v[152:155], v[176:179], v[120:123]
	v_mfma_f32_16x16x32_bf16 v[108:111], v[144:147], v[184:187], v[108:111]
	v_mfma_f32_16x16x32_bf16 v[104:107], v[152:155], v[184:187], v[104:107]
	v_mfma_f32_16x16x32_bf16 v[92:95], v[144:147], v[192:195], v[92:95]
	v_mfma_f32_16x16x32_bf16 v[88:91], v[152:155], v[192:195], v[88:91]
	v_mfma_f32_16x16x32_bf16 v[76:79], v[144:147], v[200:203], v[76:79]
	v_mfma_f32_16x16x32_bf16 v[72:75], v[152:155], v[200:203], v[72:75]
	v_mfma_f32_16x16x32_bf16 v[124:127], v[148:151], v[180:183], v[124:127]
	v_mfma_f32_16x16x32_bf16 v[120:123], v[156:159], v[180:183], v[120:123]
	v_mfma_f32_16x16x32_bf16 v[108:111], v[148:151], v[188:191], v[108:111]
	v_mfma_f32_16x16x32_bf16 v[104:107], v[156:159], v[188:191], v[104:107]
	v_mfma_f32_16x16x32_bf16 v[92:95], v[148:151], v[196:199], v[92:95]
	v_mfma_f32_16x16x32_bf16 v[88:91], v[156:159], v[196:199], v[88:91]
	v_mfma_f32_16x16x32_bf16 v[76:79], v[148:151], v[204:207], v[76:79]
	v_mfma_f32_16x16x32_bf16 v[72:75], v[156:159], v[204:207], v[72:75]
	s_setprio 0
	s_setprio 1
	v_mfma_f32_16x16x32_bf16 v[116:119], v[160:163], v[176:179], v[116:119]
	v_mfma_f32_16x16x32_bf16 v[112:115], v[168:171], v[176:179], v[112:115]
	v_mfma_f32_16x16x32_bf16 v[100:103], v[160:163], v[184:187], v[100:103]
	v_mfma_f32_16x16x32_bf16 v[96:99], v[168:171], v[184:187], v[96:99]
	v_mfma_f32_16x16x32_bf16 v[84:87], v[160:163], v[192:195], v[84:87]
	v_mfma_f32_16x16x32_bf16 v[80:83], v[168:171], v[192:195], v[80:83]
	v_mfma_f32_16x16x32_bf16 v[68:71], v[160:163], v[200:203], v[68:71]
	v_mfma_f32_16x16x32_bf16 v[64:67], v[168:171], v[200:203], v[64:67]
	v_mfma_f32_16x16x32_bf16 v[116:119], v[164:167], v[180:183], v[116:119]
	v_mfma_f32_16x16x32_bf16 v[112:115], v[172:175], v[180:183], v[112:115]
	v_mfma_f32_16x16x32_bf16 v[100:103], v[164:167], v[188:191], v[100:103]
	v_mfma_f32_16x16x32_bf16 v[96:99], v[172:175], v[188:191], v[96:99]
	v_mfma_f32_16x16x32_bf16 v[84:87], v[164:167], v[196:199], v[84:87]
	v_mfma_f32_16x16x32_bf16 v[80:83], v[172:175], v[196:199], v[80:83]
	v_mfma_f32_16x16x32_bf16 v[68:71], v[164:167], v[204:207], v[68:71]
	v_mfma_f32_16x16x32_bf16 v[64:67], v[172:175], v[204:207], v[64:67]
	s_setprio 0
	s_barrier
; #define PG8_STAGE(bufoff, gbase, voff) do { _Pragma("unroll") for (int _i = 0; _i < 2; ++_i) \
;         __builtin_amdgcn_global_load_lds((const unsigned*)((const char*)(gbase) + (voff)[_i]), (PG8_LAS unsigned*)(lds + (bufoff) + ldsw + _i * 8192), 16, 0, 0); } while (0)
; #define PG8_LDA(dst, b, h) do { _Pragma("unroll") for (int m = 0; m < 4; ++m) _Pragma("unroll") for (int k = 0; k < 2; ++k) dst[m][k] = *(const PG8_LAS bf16x8*)(lds + PG8_SA(b, h) + aoff + m * 2048 + k * 1024); } while (0)
; #define PG8_MMA(ai, bj, At, Bt) do { __builtin_amdgcn_s_setprio(1); _Pragma("unroll") for (int m = 0; m < 4; ++m) _Pragma("unroll") for (int n = 0; n < 2; ++n) _Pragma("unroll") for (int k = 0; k < 2; ++k) \
;         acc[ai][bj][m][n] = __builtin_amdgcn_mfma_f32_16x16x32_bf16(Bt[n][k], At[m][k], acc[ai][bj][m][n], 0, 0, 0); __builtin_amdgcn_s_setprio(0); } while (0)
; #define PG8_WAIT_V(n) asm volatile("s_waitcnt vmcnt(" #n ")" ::: "memory")
; #define PG8_WAIT_L(n) asm volatile("s_waitcnt lgkmcnt(" #n ")" ::: "memory")
; #define PG8_BAR __builtin_amdgcn_s_barrier()
; #define PG8_SCHED __builtin_amdgcn_sched_barrier(0)
; template <class Epi>
; DI void gemm_phase(PG8_LAS unsigned char* lds, const Gemm g, const StaticOrder& S, const Epi& E) {
;     ...
;         for (int t = 0; t < nt; t += 2) {
;     ...
;             PG8_LDA(At, 1, 1); PG8_STAGE(PG8_SB(1, 0), b3, voffB); PG8_STAGE(PG8_SB(1, 1), b3 + hstepB, voffB); PG8_STAGE(PG8_SA(1, 0), a3, voffA);
;             PG8_WAIT_V(8); PG8_WAIT_L(0); PG8_BAR; PG8_MMA(1, 0, At, B0); PG8_MMA(1, 1, At, B1); PG8_BAR; PG8_SCHED;
;         }
	s_add_i32 s20, s58, s29
	v_lshl_add_u64 v[214:215], v[214:215], 0, s[12:13]
	s_mov_b32 m0, s20
	ds_read_b128 v[176:179], v213 offset:49152
	ds_read_b128 v[180:183], v213 offset:50176
	ds_read_b128 v[184:187], v213 offset:51200
	ds_read_b128 v[188:191], v213 offset:52224
	ds_read_b128 v[192:195], v213 offset:53248
	ds_read_b128 v[196:199], v213 offset:54272
	ds_read_b128 v[200:203], v213 offset:55296
	ds_read_b128 v[204:207], v213 offset:56320
	global_load_lds_dwordx4 v[214:215], off
	s_add_i32 m0, s20, 0x2000
	s_add_u32 s20, s24, 0xb0080
	v_lshl_add_u64 v[214:215], v[216:217], 0, s[12:13]
	s_addc_u32 s21, s25, 0
	s_add_i32 s24, s59, s29
	global_load_lds_dwordx4 v[214:215], off
	v_lshl_add_u64 v[214:215], s[20:21], 0, v[130:131]
	s_mov_b32 m0, s24
	s_nop 0
	global_load_lds_dwordx4 v[214:215], off
	v_lshl_add_u64 v[214:215], s[20:21], 0, v[134:135]
	s_add_i32 m0, s24, 0x2000
	s_nop 0
	global_load_lds_dwordx4 v[214:215], off
	v_lshl_add_u64 v[214:215], v[218:219], 0, s[12:13]
	s_mov_b32 m0, s39
	s_nop 0
	global_load_lds_dwordx4 v[214:215], off
	v_lshl_add_u64 v[214:215], v[220:221], 0, s[12:13]
	s_mov_b32 m0, s40
	s_nop 0
	global_load_lds_dwordx4 v[214:215], off
	s_waitcnt vmcnt(8)
	s_waitcnt lgkmcnt(0)
	s_barrier
	s_setprio 1
	s_waitcnt lgkmcnt(0)
	v_mfma_f32_16x16x32_bf16 v[60:63], v[144:147], v[176:179], v[60:63]
	v_mfma_f32_16x16x32_bf16 v[56:59], v[152:155], v[176:179], v[56:59]
	v_mfma_f32_16x16x32_bf16 v[44:47], v[144:147], v[184:187], v[44:47]
	v_mfma_f32_16x16x32_bf16 v[40:43], v[152:155], v[184:187], v[40:43]
	v_mfma_f32_16x16x32_bf16 v[32:35], v[144:147], v[192:195], v[32:35]
	v_mfma_f32_16x16x32_bf16 v[24:27], v[152:155], v[192:195], v[24:27]
	v_mfma_f32_16x16x32_bf16 v[12:15], v[144:147], v[200:203], v[12:15]
	v_mfma_f32_16x16x32_bf16 v[8:11], v[152:155], v[200:203], v[8:11]
	v_mfma_f32_16x16x32_bf16 v[60:63], v[148:151], v[180:183], v[60:63]
	v_mfma_f32_16x16x32_bf16 v[56:59], v[156:159], v[180:183], v[56:59]
	v_mfma_f32_16x16x32_bf16 v[44:47], v[148:151], v[188:191], v[44:47]
	v_mfma_f32_16x16x32_bf16 v[40:43], v[156:159], v[188:191], v[40:43]
	v_mfma_f32_16x16x32_bf16 v[32:35], v[148:151], v[196:199], v[32:35]
	v_mfma_f32_16x16x32_bf16 v[24:27], v[156:159], v[196:199], v[24:27]
	v_mfma_f32_16x16x32_bf16 v[12:15], v[148:151], v[204:207], v[12:15]
	v_mfma_f32_16x16x32_bf16 v[8:11], v[156:159], v[204:207], v[8:11]
	s_setprio 0
	s_setprio 1
	v_mfma_f32_16x16x32_bf16 v[52:55], v[160:163], v[176:179], v[52:55]
	v_mfma_f32_16x16x32_bf16 v[48:51], v[168:171], v[176:179], v[48:51]
	v_mfma_f32_16x16x32_bf16 v[36:39], v[160:163], v[184:187], v[36:39]
	v_mfma_f32_16x16x32_bf16 v[28:31], v[168:171], v[184:187], v[28:31]
	v_mfma_f32_16x16x32_bf16 v[20:23], v[160:163], v[192:195], v[20:23]
	v_mfma_f32_16x16x32_bf16 v[16:19], v[168:171], v[192:195], v[16:19]
	v_mfma_f32_16x16x32_bf16 v[4:7], v[160:163], v[200:203], v[4:7]
	v_mfma_f32_16x16x32_bf16 v[0:3], v[168:171], v[200:203], v[0:3]
	v_mfma_f32_16x16x32_bf16 v[52:55], v[164:167], v[180:183], v[52:55]
	v_mfma_f32_16x16x32_bf16 v[48:51], v[172:175], v[180:183], v[48:51]
	v_mfma_f32_16x16x32_bf16 v[36:39], v[164:167], v[188:191], v[36:39]
	v_mfma_f32_16x16x32_bf16 v[28:31], v[172:175], v[188:191], v[28:31]
	v_mfma_f32_16x16x32_bf16 v[20:23], v[164:167], v[196:199], v[20:23]
	v_mfma_f32_16x16x32_bf16 v[16:19], v[172:175], v[196:199], v[16:19]
	v_mfma_f32_16x16x32_bf16 v[4:7], v[164:167], v[204:207], v[4:7]
	v_mfma_f32_16x16x32_bf16 v[0:3], v[172:175], v[204:207], v[0:3]
	s_setprio 0
	s_add_i32 s57, s57, 2
	s_add_u32 s55, s55, 0x100
	s_addc_u32 s56, s56, 0
	s_cmp_gt_u32 s57, 41
	s_mov_b64 s[20:21], s[22:23]
	s_barrier
	s_cbranch_scc0 .LBB0_1224
	s_and_b64 vcc, exec, s[14:15]
	s_cbranch_vccz .LBB0_1227
	s_barrier
